# P0 de-serialised: W_in/W_out item loads 32 in flight per half-item instead of 2; all 16 per-row gain loads issued together (3 copies); on top of K-loop segment-head edit, down-proj full-line stores, a
# speedup vs baseline: 1.0229x; 1.0122x over previous
.LBB0_23:
	s_andn2_b64 vcc, exec, s[0:1]
	v_mov_b32_e32 v2, 0
	s_cbranch_vccnz .LBB0_25
	s_add_i32 s28, s9, 0xffffa000
	s_lshl_b64 s[0:1], s[28:29], 14
	v_lshl_add_u64 v[0:1], v[126:127], 0, s[0:1]
	v_add_co_u32_e32 v2, vcc, s40, v0
	global_load_dwordx4 v[60:63], v[0:1], off
	global_load_dwordx4 v[56:59], v[0:1], off offset:1024
	global_load_dwordx4 v[52:55], v[0:1], off offset:2048
	global_load_dwordx4 v[48:51], v[0:1], off offset:3072
	v_addc_co_u32_e32 v3, vcc, 0, v1, vcc
	global_load_dwordx4 v[44:47], v[2:3], off offset:-4096
	v_add_co_u32_e32 v4, vcc, s7, v0
	s_and_b32 s28, s3, 0x7f80
	s_nop 0
	v_addc_co_u32_e32 v5, vcc, 0, v1, vcc
	global_load_dwordx4 v[40:43], v[4:5], off offset:1024
	global_load_dwordx4 v[36:39], v[4:5], off offset:2048
	global_load_dwordx4 v[32:35], v[4:5], off offset:3072
	global_load_dwordx4 v[28:31], v[2:3], off
	global_load_dwordx4 v[24:27], v[2:3], off offset:1024
	global_load_dwordx4 v[20:23], v[2:3], off offset:2048
	global_load_dwordx4 v[16:19], v[2:3], off offset:3072
	v_add_co_u32_e32 v0, vcc, s41, v0
	s_waitcnt vmcnt(11)
	v_mul_f32_e32 v67, v61, v61
	v_addc_co_u32_e32 v1, vcc, 0, v1, vcc
	global_load_dwordx4 v[12:15], v[0:1], off
	global_load_dwordx4 v[8:11], v[0:1], off offset:1024
	global_load_dwordx4 v[4:7], v[0:1], off offset:2048
	s_nop 0
	global_load_dwordx4 v[0:3], v[0:1], off offset:3072
	v_mul_f32_e32 v69, v63, v63
	s_waitcnt vmcnt(14)
	v_mul_f32_e32 v138, v57, v57
	v_mul_f32_e32 v139, v59, v59
	s_waitcnt vmcnt(13)
	v_mul_f32_e32 v145, v53, v53
	v_mul_f32_e32 v146, v55, v55
	v_fmac_f32_e32 v67, v60, v60
	v_fmac_f32_e32 v69, v62, v62
	v_fmac_f32_e32 v138, v56, v56
	v_fmac_f32_e32 v139, v58, v58
	s_waitcnt vmcnt(12)
	v_mul_f32_e32 v147, v49, v49
	v_mul_f32_e32 v148, v51, v51
	v_fmac_f32_e32 v145, v52, v52
	v_fmac_f32_e32 v146, v54, v54
	v_add_f32_e32 v67, v67, v69
	v_add_f32_e32 v69, v138, v139
	v_fmac_f32_e32 v147, v48, v48
	v_fmac_f32_e32 v148, v50, v50
	s_waitcnt vmcnt(11)
	v_mul_f32_e32 v149, v45, v45
	v_mul_f32_e32 v150, v47, v47
	v_add_f32_e32 v138, v145, v146
	v_add_f32_e32 v67, v67, v69
	s_waitcnt vmcnt(10)
	v_mul_f32_e32 v151, v41, v41
	v_mul_f32_e32 v152, v43, v43
	v_add_f32_e32 v139, v147, v148
	v_fmac_f32_e32 v149, v44, v44
	v_fmac_f32_e32 v150, v46, v46
	v_add_f32_e32 v67, v67, v138
	s_waitcnt vmcnt(9)
	v_mul_f32_e32 v153, v37, v37
	v_mul_f32_e32 v154, v39, v39
	v_fmac_f32_e32 v151, v40, v40
	v_fmac_f32_e32 v152, v42, v42
	v_add_f32_e32 v69, v149, v150
	v_add_f32_e32 v67, v67, v139
	s_waitcnt vmcnt(8)
	v_mul_f32_e32 v155, v33, v33
	v_mul_f32_e32 v156, v35, v35
	v_fmac_f32_e32 v153, v36, v36
	v_fmac_f32_e32 v154, v38, v38
	v_add_f32_e32 v145, v151, v152
	v_add_f32_e32 v67, v67, v69
	s_waitcnt vmcnt(7)
	v_mul_f32_e32 v157, v29, v29
	v_mul_f32_e32 v158, v31, v31
	v_fmac_f32_e32 v155, v32, v32
	v_fmac_f32_e32 v156, v34, v34
	v_add_f32_e32 v146, v153, v154
	v_add_f32_e32 v67, v67, v145
	s_waitcnt vmcnt(6)
	v_mul_f32_e32 v159, v25, v25
	v_mul_f32_e32 v160, v27, v27
	v_fmac_f32_e32 v157, v28, v28
	v_fmac_f32_e32 v158, v30, v30
	v_add_f32_e32 v147, v155, v156
	v_add_f32_e32 v67, v67, v146
	s_waitcnt vmcnt(5)
	v_mul_f32_e32 v161, v21, v21
	v_mul_f32_e32 v162, v23, v23
	v_fmac_f32_e32 v159, v24, v24
	v_fmac_f32_e32 v160, v26, v26
	v_add_f32_e32 v148, v157, v158
	v_add_f32_e32 v67, v67, v147
	v_fmac_f32_e32 v161, v20, v20
	v_fmac_f32_e32 v162, v22, v22
	v_add_f32_e32 v149, v159, v160
	v_add_f32_e32 v67, v67, v148
	s_waitcnt vmcnt(4)
	v_mul_f32_e32 v69, v17, v17
	v_mul_f32_e32 v138, v19, v19
	v_add_f32_e32 v150, v161, v162
	v_add_f32_e32 v67, v67, v149
	v_fmac_f32_e32 v69, v16, v16
	v_fmac_f32_e32 v138, v18, v18
	v_add_f32_e32 v67, v67, v150
	v_add_f32_e32 v69, v69, v138
	v_add_f32_e32 v67, v67, v69
	v_mov_b32_e32 v230, 0x1000
	v_mov_b32_e32 v231, 0
	v_lshl_add_u64 v[228:229], v[72:73], 0, v[230:231]
	v_lshl_add_u64 v[232:233], v[228:229], 0, v[230:231]
	v_lshl_add_u64 v[234:235], v[232:233], 0, v[230:231]
	global_load_dwordx4 v[164:167], v[72:73], off
	global_load_dwordx4 v[168:171], v[72:73], off offset:1024
	global_load_dwordx4 v[172:175], v[72:73], off offset:2048
	global_load_dwordx4 v[176:179], v[72:73], off offset:3072
	global_load_dwordx4 v[180:183], v[228:229], off
	global_load_dwordx4 v[184:187], v[228:229], off offset:1024
	global_load_dwordx4 v[188:191], v[228:229], off offset:2048
	global_load_dwordx4 v[192:195], v[228:229], off offset:3072
	global_load_dwordx4 v[196:199], v[232:233], off
	global_load_dwordx4 v[200:203], v[232:233], off offset:1024
	global_load_dwordx4 v[204:207], v[232:233], off offset:2048
	global_load_dwordx4 v[208:211], v[232:233], off offset:3072
	global_load_dwordx4 v[212:215], v[234:235], off
	global_load_dwordx4 v[216:219], v[234:235], off offset:1024
	global_load_dwordx4 v[220:223], v[234:235], off offset:2048
	global_load_dwordx4 v[224:227], v[234:235], off offset:3072
	s_waitcnt vmcnt(19)
	v_mul_f32_e32 v69, v13, v13
	v_mul_f32_e32 v138, v15, v15
	v_fmac_f32_e32 v69, v12, v12
	v_fmac_f32_e32 v138, v14, v14
	v_add_f32_e32 v69, v69, v138
	v_add_f32_e32 v67, v67, v69
	s_waitcnt vmcnt(18)
	v_mul_f32_e32 v69, v9, v9
	v_mul_f32_e32 v138, v11, v11
	v_fmac_f32_e32 v69, v8, v8
	v_fmac_f32_e32 v138, v10, v10
	v_add_f32_e32 v69, v69, v138
	v_add_f32_e32 v67, v67, v69
	s_waitcnt vmcnt(17)
	v_mul_f32_e32 v69, v5, v5
	v_mul_f32_e32 v138, v7, v7
	v_fmac_f32_e32 v69, v4, v4
	v_fmac_f32_e32 v138, v6, v6
	v_add_f32_e32 v69, v69, v138
	v_add_f32_e32 v67, v67, v69
	s_waitcnt vmcnt(16)
	v_mul_f32_e32 v69, v1, v1
	v_mul_f32_e32 v138, v3, v3
	v_fmac_f32_e32 v69, v0, v0
	v_fmac_f32_e32 v138, v2, v2
	v_add_f32_e32 v69, v69, v138
	v_add_f32_e32 v67, v67, v69
	v_and_b32_e32 v69, 64, v142
	v_add_u32_e32 v69, 64, v69
	v_xor_b32_e32 v138, 1, v142
	v_cmp_lt_i32_e32 vcc, v138, v69
	s_nop 1
	v_cndmask_b32_e32 v138, v142, v138, vcc
	v_lshlrev_b32_e32 v138, 2, v138
	ds_bpermute_b32 v138, v138, v67
	s_waitcnt lgkmcnt(0)
	v_add_f32_e32 v67, v67, v138
	v_xor_b32_e32 v138, 2, v142
	v_cmp_lt_i32_e32 vcc, v138, v69
	s_nop 1
	v_cndmask_b32_e32 v138, v142, v138, vcc
	v_lshlrev_b32_e32 v138, 2, v138
	ds_bpermute_b32 v138, v138, v67
	s_waitcnt lgkmcnt(0)
	v_add_f32_e32 v67, v67, v138
	v_xor_b32_e32 v138, 4, v142
	v_cmp_lt_i32_e32 vcc, v138, v69
	s_nop 1
	v_cndmask_b32_e32 v138, v142, v138, vcc
	v_lshlrev_b32_e32 v138, 2, v138
	ds_bpermute_b32 v138, v138, v67
	s_waitcnt lgkmcnt(0)
	v_add_f32_e32 v67, v67, v138
	v_xor_b32_e32 v138, 8, v142
	v_cmp_lt_i32_e32 vcc, v138, v69
	s_nop 1
	v_cndmask_b32_e32 v138, v142, v138, vcc
	v_lshlrev_b32_e32 v138, 2, v138
	ds_bpermute_b32 v138, v138, v67
	s_waitcnt lgkmcnt(0)
	v_add_f32_e32 v67, v67, v138
	v_xor_b32_e32 v138, 16, v142
	v_cmp_lt_i32_e32 vcc, v138, v69
	s_nop 1
	v_cndmask_b32_e32 v138, v142, v138, vcc
	v_lshlrev_b32_e32 v138, 2, v138
	ds_bpermute_b32 v138, v138, v67
	s_waitcnt lgkmcnt(0)
	v_add_f32_e32 v67, v67, v138
	v_xor_b32_e32 v138, 32, v142
	v_cmp_lt_i32_e32 vcc, v138, v69
	s_nop 1
	v_cndmask_b32_e32 v69, v142, v138, vcc
	v_lshlrev_b32_e32 v69, 2, v69
	ds_bpermute_b32 v69, v69, v67
	s_waitcnt lgkmcnt(0)
	v_add_f32_e32 v67, v67, v69
	v_fmamk_f32 v67, v67, 0x39800000, v140
	v_mul_f32_e32 v69, 0x4f800000, v67
	v_cmp_gt_f32_e32 vcc, s42, v67
	s_nop 1
	v_cndmask_b32_e32 v67, v67, v69, vcc
	v_sqrt_f32_e32 v69, v67
	s_nop 0
	v_add_u32_e32 v138, -1, v69
	v_fma_f32 v139, -v138, v69, v67
	v_cmp_ge_f32_e64 s[0:1], 0, v139
	v_add_u32_e32 v139, 1, v69
	s_nop 0
	v_cndmask_b32_e64 v138, v69, v138, s[0:1]
	v_fma_f32 v69, -v139, v69, v67
	v_cmp_lt_f32_e64 s[0:1], 0, v69
	s_nop 1
	v_cndmask_b32_e64 v69, v138, v139, s[0:1]
	v_mul_f32_e32 v138, 0x37800000, v69
	v_cndmask_b32_e32 v69, v69, v138, vcc
	v_cmp_class_f32_e32 vcc, v67, v141
	s_nop 1
	v_cndmask_b32_e32 v67, v69, v67, vcc
	v_div_scale_f32 v69, s[0:1], v67, v67, s43
	v_rcp_f32_e32 v138, v69
	s_nop 0
	v_fma_f32 v139, -v69, v138, 1.0
	v_fmac_f32_e32 v138, v139, v138
	v_div_scale_f32 v139, vcc, s43, v67, s43
	v_mul_f32_e32 v145, v139, v138
	v_fma_f32 v150, -v69, v145, v139
	v_fmac_f32_e32 v145, v150, v138
	v_fma_f32 v69, -v69, v145, v139
	v_div_fmas_f32 v69, v69, v138, v145
	v_div_fixup_f32 v67, v69, v67, s43
	v_mul_f32_e32 v60, v60, v67
	v_mul_f32_e32 v61, v61, v67
	v_mul_f32_e32 v62, v62, v67
	v_mul_f32_e32 v63, v63, v67
	s_waitcnt vmcnt(0)
	v_mul_f32_e32 v60, v164, v60
	v_mul_f32_e32 v61, v165, v61
	v_mul_f32_e32 v62, v166, v62
	v_mul_f32_e32 v63, v167, v63
	v_med3_f32 v60, v60, s44, v143
	v_med3_f32 v61, v61, s44, v143
	v_med3_f32 v62, v62, s44, v143
	v_med3_f32 v63, v63, s44, v143
	v_add_f32_e32 v60, 0x4b400000, v60
	v_add_f32_e32 v61, 0x4b400000, v61
	v_add_f32_e32 v62, 0x4b400000, v62
	v_add_f32_e32 v63, 0x4b400000, v63
	v_perm_b32 v60, v61, v60, s45
	v_perm_b32 v61, v63, v62, s45
	v_lshl_add_u64 v[138:139], v[124:125], 0, s[28:29]
	v_lshl_or_b32 v60, v61, 16, v60
	global_store_dword v[138:139], v60, off
	v_mul_f32_e32 v56, v56, v67
	v_mul_f32_e32 v57, v57, v67
	v_mul_f32_e32 v58, v58, v67
	v_mul_f32_e32 v59, v59, v67
	v_add_co_u32_e32 v146, vcc, s46, v138
	v_mul_f32_e32 v52, v52, v67
	s_nop 0
	v_addc_co_u32_e32 v147, vcc, 0, v139, vcc
	v_mul_f32_e32 v53, v53, v67
	v_mul_f32_e32 v54, v54, v67
	v_mul_f32_e32 v55, v55, v67
	v_mul_f32_e32 v48, v48, v67
	v_mul_f32_e32 v49, v49, v67
	v_mul_f32_e32 v50, v50, v67
	v_mul_f32_e32 v51, v51, v67
	v_mul_f32_e32 v44, v44, v67
	v_mul_f32_e32 v45, v45, v67
	v_mul_f32_e32 v46, v46, v67
	v_mul_f32_e32 v47, v47, v67
	v_mul_f32_e32 v40, v40, v67
	v_mul_f32_e32 v41, v41, v67
	v_mul_f32_e32 v42, v42, v67
	v_mul_f32_e32 v43, v43, v67
	v_mul_f32_e32 v36, v36, v67
	v_mul_f32_e32 v37, v37, v67
	v_mul_f32_e32 v38, v38, v67
	v_mul_f32_e32 v39, v39, v67
	v_mul_f32_e32 v32, v32, v67
	v_mul_f32_e32 v33, v33, v67
	v_mul_f32_e32 v34, v34, v67
	v_mul_f32_e32 v35, v35, v67
	v_mul_f32_e32 v28, v28, v67
	v_mul_f32_e32 v29, v29, v67
	v_mul_f32_e32 v30, v30, v67
	v_mul_f32_e32 v31, v31, v67
	v_mul_f32_e32 v24, v24, v67
	v_mul_f32_e32 v25, v25, v67
	v_mul_f32_e32 v26, v26, v67
	v_mul_f32_e32 v27, v27, v67
	v_mul_f32_e32 v20, v20, v67
	v_mul_f32_e32 v21, v21, v67
	v_mul_f32_e32 v22, v22, v67
	v_mul_f32_e32 v23, v23, v67
	v_mul_f32_e32 v16, v16, v67
	v_mul_f32_e32 v17, v17, v67
	v_mul_f32_e32 v18, v18, v67
	v_mul_f32_e32 v19, v19, v67
	v_mul_f32_e32 v12, v12, v67
	v_mul_f32_e32 v13, v13, v67
	v_mul_f32_e32 v14, v14, v67
	v_mul_f32_e32 v15, v15, v67
	v_mul_f32_e32 v8, v8, v67
	v_mul_f32_e32 v9, v9, v67
	v_mul_f32_e32 v10, v10, v67
	v_mul_f32_e32 v11, v11, v67
	v_mul_f32_e32 v4, v4, v67
	v_mul_f32_e32 v5, v5, v67
	v_mul_f32_e32 v6, v6, v67
	v_mul_f32_e32 v7, v7, v67
	v_mul_f32_e32 v0, v0, v67
	v_mul_f32_e32 v1, v1, v67
	v_mul_f32_e32 v2, v2, v67
	v_mul_f32_e32 v3, v3, v67
	v_mul_f32_e32 v56, v168, v56
	v_mul_f32_e32 v57, v169, v57
	v_mul_f32_e32 v58, v170, v58
	v_mul_f32_e32 v59, v171, v59
	v_med3_f32 v56, v56, s44, v143
	v_med3_f32 v57, v57, s44, v143
	v_med3_f32 v58, v58, s44, v143
	v_med3_f32 v59, v59, s44, v143
	v_add_f32_e32 v56, 0x4b400000, v56
	v_add_f32_e32 v57, 0x4b400000, v57
	v_add_f32_e32 v58, 0x4b400000, v58
	v_add_f32_e32 v59, 0x4b400000, v59
	v_perm_b32 v56, v57, v56, s45
	v_perm_b32 v57, v59, v58, s45
	v_lshl_or_b32 v56, v57, 16, v56
	global_store_dword v[146:147], v56, off
	v_add_co_u32_e32 v60, vcc, s47, v138
	v_mul_f32_e32 v52, v172, v52
	v_mul_f32_e32 v53, v173, v53
	v_mul_f32_e32 v54, v174, v54
	v_mul_f32_e32 v55, v175, v55
	v_med3_f32 v52, v52, s44, v143
	v_med3_f32 v53, v53, s44, v143
	v_med3_f32 v54, v54, s44, v143
	v_med3_f32 v55, v55, s44, v143
	v_add_f32_e32 v52, 0x4b400000, v52
	v_add_f32_e32 v53, 0x4b400000, v53
	v_add_f32_e32 v54, 0x4b400000, v54
	v_add_f32_e32 v55, 0x4b400000, v55
	v_perm_b32 v52, v53, v52, s45
	v_perm_b32 v53, v55, v54, s45
	v_addc_co_u32_e32 v61, vcc, 0, v139, vcc
	v_lshl_or_b32 v52, v53, 16, v52
	global_store_dword v[60:61], v52, off
	v_add_co_u32_e32 v56, vcc, s49, v138
	v_mul_f32_e32 v48, v176, v48
	v_mul_f32_e32 v49, v177, v49
	v_mul_f32_e32 v50, v178, v50
	v_mul_f32_e32 v51, v179, v51
	v_med3_f32 v48, v48, s44, v143
	v_med3_f32 v49, v49, s44, v143
	v_med3_f32 v50, v50, s44, v143
	v_med3_f32 v51, v51, s44, v143
	v_add_f32_e32 v48, 0x4b400000, v48
	v_add_f32_e32 v49, 0x4b400000, v49
	v_add_f32_e32 v50, 0x4b400000, v50
	v_add_f32_e32 v51, 0x4b400000, v51
	v_perm_b32 v48, v49, v48, s45
	v_perm_b32 v49, v51, v50, s45
	v_addc_co_u32_e32 v57, vcc, 0, v139, vcc
	v_lshl_or_b32 v48, v49, 16, v48
	global_store_dword v[56:57], v48, off
	v_add_co_u32_e32 v52, vcc, s50, v138
	v_mul_f32_e32 v44, v44, v180
	v_mul_f32_e32 v45, v45, v181
	v_mul_f32_e32 v46, v46, v182
	v_mul_f32_e32 v47, v47, v183
	v_med3_f32 v44, v44, s44, v143
	v_med3_f32 v45, v45, s44, v143
	v_med3_f32 v46, v46, s44, v143
	v_med3_f32 v47, v47, s44, v143
	v_add_f32_e32 v44, 0x4b400000, v44
	v_add_f32_e32 v45, 0x4b400000, v45
	v_add_f32_e32 v46, 0x4b400000, v46
	v_add_f32_e32 v47, 0x4b400000, v47
	v_perm_b32 v44, v45, v44, s45
	v_perm_b32 v45, v47, v46, s45
	v_addc_co_u32_e32 v53, vcc, 0, v139, vcc
	v_lshl_or_b32 v44, v45, 16, v44
	global_store_dword v[52:53], v44, off
	v_add_co_u32_e32 v48, vcc, s51, v138
	v_mul_f32_e32 v40, v40, v184
	v_mul_f32_e32 v41, v41, v185
	v_mul_f32_e32 v42, v42, v186
	v_mul_f32_e32 v43, v43, v187
	v_med3_f32 v40, v40, s44, v143
	v_med3_f32 v41, v41, s44, v143
	v_med3_f32 v42, v42, s44, v143
	v_med3_f32 v43, v43, s44, v143
	v_add_f32_e32 v40, 0x4b400000, v40
	v_add_f32_e32 v41, 0x4b400000, v41
	v_add_f32_e32 v42, 0x4b400000, v42
	v_add_f32_e32 v43, 0x4b400000, v43
	v_perm_b32 v40, v41, v40, s45
	v_perm_b32 v41, v43, v42, s45
	v_addc_co_u32_e32 v49, vcc, 0, v139, vcc
	v_lshl_or_b32 v40, v41, 16, v40
	global_store_dword v[48:49], v40, off
	v_add_co_u32_e32 v44, vcc, s52, v138
	v_mul_f32_e32 v36, v36, v188
	v_mul_f32_e32 v37, v37, v189
	v_mul_f32_e32 v38, v38, v190
	v_mul_f32_e32 v39, v39, v191
	v_med3_f32 v36, v36, s44, v143
	v_med3_f32 v37, v37, s44, v143
	v_med3_f32 v38, v38, s44, v143
	v_med3_f32 v39, v39, s44, v143
	v_add_f32_e32 v36, 0x4b400000, v36
	v_add_f32_e32 v37, 0x4b400000, v37
	v_add_f32_e32 v38, 0x4b400000, v38
	v_add_f32_e32 v39, 0x4b400000, v39
	v_perm_b32 v36, v37, v36, s45
	v_perm_b32 v37, v39, v38, s45
	v_addc_co_u32_e32 v45, vcc, 0, v139, vcc
	v_lshl_or_b32 v36, v37, 16, v36
	global_store_dword v[44:45], v36, off
	v_add_co_u32_e32 v40, vcc, s53, v138
	v_mul_f32_e32 v32, v32, v192
	v_mul_f32_e32 v33, v33, v193
	v_mul_f32_e32 v34, v34, v194
	v_mul_f32_e32 v35, v35, v195
	v_med3_f32 v32, v32, s44, v143
	v_med3_f32 v33, v33, s44, v143
	v_med3_f32 v34, v34, s44, v143
	v_med3_f32 v35, v35, s44, v143
	v_add_f32_e32 v32, 0x4b400000, v32
	v_add_f32_e32 v33, 0x4b400000, v33
	v_add_f32_e32 v34, 0x4b400000, v34
	v_add_f32_e32 v35, 0x4b400000, v35
	v_perm_b32 v32, v33, v32, s45
	v_perm_b32 v33, v35, v34, s45
	v_addc_co_u32_e32 v41, vcc, 0, v139, vcc
	v_lshl_or_b32 v32, v33, 16, v32
	global_store_dword v[40:41], v32, off
	v_add_co_u32_e32 v36, vcc, s54, v138
	v_mul_f32_e32 v28, v28, v196
	v_mul_f32_e32 v29, v29, v197
	v_mul_f32_e32 v30, v30, v198
	v_mul_f32_e32 v31, v31, v199
	v_med3_f32 v28, v28, s44, v143
	v_med3_f32 v29, v29, s44, v143
	v_med3_f32 v30, v30, s44, v143
	v_med3_f32 v31, v31, s44, v143
	v_add_f32_e32 v28, 0x4b400000, v28
	v_add_f32_e32 v29, 0x4b400000, v29
	v_add_f32_e32 v30, 0x4b400000, v30
	v_add_f32_e32 v31, 0x4b400000, v31
	v_perm_b32 v28, v29, v28, s45
	v_perm_b32 v29, v31, v30, s45
	v_addc_co_u32_e32 v37, vcc, 0, v139, vcc
	v_lshl_or_b32 v28, v29, 16, v28
	global_store_dword v[36:37], v28, off
	v_add_co_u32_e32 v32, vcc, s55, v138
	v_mul_f32_e32 v24, v24, v200
	v_mul_f32_e32 v25, v25, v201
	v_mul_f32_e32 v26, v26, v202
	v_mul_f32_e32 v27, v27, v203
	v_med3_f32 v24, v24, s44, v143
	v_med3_f32 v25, v25, s44, v143
	v_med3_f32 v26, v26, s44, v143
	v_med3_f32 v27, v27, s44, v143
	v_add_f32_e32 v24, 0x4b400000, v24
	v_add_f32_e32 v25, 0x4b400000, v25
	v_add_f32_e32 v26, 0x4b400000, v26
	v_add_f32_e32 v27, 0x4b400000, v27
	v_perm_b32 v24, v25, v24, s45
	v_perm_b32 v25, v27, v26, s45
	v_addc_co_u32_e32 v33, vcc, 0, v139, vcc
	v_lshl_or_b32 v24, v25, 16, v24
	global_store_dword v[32:33], v24, off
	v_add_co_u32_e32 v28, vcc, s56, v138
	v_mul_f32_e32 v20, v20, v204
	v_mul_f32_e32 v21, v21, v205
	v_mul_f32_e32 v22, v22, v206
	v_mul_f32_e32 v23, v23, v207
	v_med3_f32 v20, v20, s44, v143
	v_med3_f32 v21, v21, s44, v143
	v_med3_f32 v22, v22, s44, v143
	v_med3_f32 v23, v23, s44, v143
	v_add_f32_e32 v20, 0x4b400000, v20
	v_add_f32_e32 v21, 0x4b400000, v21
	v_add_f32_e32 v22, 0x4b400000, v22
	v_add_f32_e32 v23, 0x4b400000, v23
	v_perm_b32 v20, v21, v20, s45
	v_perm_b32 v21, v23, v22, s45
	v_addc_co_u32_e32 v29, vcc, 0, v139, vcc
	v_lshl_or_b32 v20, v21, 16, v20
	global_store_dword v[28:29], v20, off
	v_add_co_u32_e32 v24, vcc, s57, v138
	v_mul_f32_e32 v16, v16, v208
	v_mul_f32_e32 v17, v17, v209
	v_mul_f32_e32 v18, v18, v210
	v_mul_f32_e32 v19, v19, v211
	v_med3_f32 v16, v16, s44, v143
	v_med3_f32 v17, v17, s44, v143
	v_med3_f32 v18, v18, s44, v143
	v_med3_f32 v19, v19, s44, v143
	v_add_f32_e32 v16, 0x4b400000, v16
	v_add_f32_e32 v17, 0x4b400000, v17
	v_add_f32_e32 v18, 0x4b400000, v18
	v_add_f32_e32 v19, 0x4b400000, v19
	v_perm_b32 v16, v17, v16, s45
	v_perm_b32 v17, v19, v18, s45
	v_addc_co_u32_e32 v25, vcc, 0, v139, vcc
	v_lshl_or_b32 v16, v17, 16, v16
	global_store_dword v[24:25], v16, off
	v_add_co_u32_e32 v20, vcc, s58, v138
	v_mul_f32_e32 v12, v12, v212
	v_mul_f32_e32 v13, v13, v213
	v_mul_f32_e32 v14, v14, v214
	v_mul_f32_e32 v15, v15, v215
	v_med3_f32 v12, v12, s44, v143
	v_med3_f32 v13, v13, s44, v143
	v_med3_f32 v14, v14, s44, v143
	v_med3_f32 v15, v15, s44, v143
	v_add_f32_e32 v12, 0x4b400000, v12
	v_add_f32_e32 v13, 0x4b400000, v13
	v_add_f32_e32 v14, 0x4b400000, v14
	v_add_f32_e32 v15, 0x4b400000, v15
	v_perm_b32 v12, v13, v12, s45
	v_perm_b32 v13, v15, v14, s45
	v_addc_co_u32_e32 v21, vcc, 0, v139, vcc
	v_lshl_or_b32 v12, v13, 16, v12
	global_store_dword v[20:21], v12, off
	v_add_co_u32_e32 v16, vcc, s59, v138
	v_mul_f32_e32 v8, v8, v216
	v_mul_f32_e32 v9, v9, v217
	v_mul_f32_e32 v10, v10, v218
	v_mul_f32_e32 v11, v11, v219
	v_med3_f32 v8, v8, s44, v143
	v_med3_f32 v9, v9, s44, v143
	v_med3_f32 v10, v10, s44, v143
	v_med3_f32 v11, v11, s44, v143
	v_add_f32_e32 v8, 0x4b400000, v8
	v_add_f32_e32 v9, 0x4b400000, v9
	v_add_f32_e32 v10, 0x4b400000, v10
	v_add_f32_e32 v11, 0x4b400000, v11
	v_perm_b32 v8, v9, v8, s45
	v_perm_b32 v9, v11, v10, s45
	v_addc_co_u32_e32 v17, vcc, 0, v139, vcc
	v_lshl_or_b32 v8, v9, 16, v8
	global_store_dword v[16:17], v8, off
	v_add_co_u32_e32 v12, vcc, s60, v138
	v_mul_f32_e32 v4, v4, v220
	v_mul_f32_e32 v5, v5, v221
	v_mul_f32_e32 v6, v6, v222
	v_mul_f32_e32 v7, v7, v223
	v_med3_f32 v4, v4, s44, v143
	v_med3_f32 v5, v5, s44, v143
	v_med3_f32 v6, v6, s44, v143
	v_med3_f32 v7, v7, s44, v143
	v_add_f32_e32 v4, 0x4b400000, v4
	v_add_f32_e32 v5, 0x4b400000, v5
	v_add_f32_e32 v6, 0x4b400000, v6
	v_add_f32_e32 v7, 0x4b400000, v7
	v_perm_b32 v4, v5, v4, s45
	v_perm_b32 v5, v7, v6, s45
	v_addc_co_u32_e32 v13, vcc, 0, v139, vcc
	v_lshl_or_b32 v4, v5, 16, v4
	global_store_dword v[12:13], v4, off
	v_mul_f32_e32 v0, v0, v224
	v_mul_f32_e32 v1, v1, v225
	v_mul_f32_e32 v2, v2, v226
	v_mul_f32_e32 v3, v3, v227
	v_med3_f32 v0, v0, s44, v143
	v_med3_f32 v1, v1, s44, v143
	v_med3_f32 v2, v2, s44, v143
	v_med3_f32 v3, v3, s44, v143
	v_add_f32_e32 v0, 0x4b400000, v0
	v_add_f32_e32 v1, 0x4b400000, v1
	v_add_f32_e32 v2, 0x4b400000, v2
	v_add_f32_e32 v3, 0x4b400000, v3
	v_perm_b32 v0, v1, v0, s45
	v_perm_b32 v1, v3, v2, s45
	v_lshl_or_b32 v2, v1, 16, v0
	v_lshl_add_u64 v[0:1], v[138:139], 0, s[34:35]

.LBB0_26:
	s_andn2_b64 vcc, exec, s[0:1]
	s_cbranch_vccnz .LBB0_28
	s_add_i32 s28, s9, 0xffffe000
	s_lshl_b64 s[0:1], s[28:29], 14
	v_lshl_add_u64 v[0:1], v[128:129], 0, s[0:1]
	v_add_co_u32_e32 v2, vcc, s40, v0
	global_load_dwordx4 v[60:63], v[0:1], off
	global_load_dwordx4 v[56:59], v[0:1], off offset:1024
	global_load_dwordx4 v[52:55], v[0:1], off offset:2048
	global_load_dwordx4 v[48:51], v[0:1], off offset:3072
	v_addc_co_u32_e32 v3, vcc, 0, v1, vcc
	global_load_dwordx4 v[44:47], v[2:3], off offset:-4096
	v_add_co_u32_e32 v4, vcc, s7, v0
	s_and_b32 s28, s3, 0x7f80
	s_nop 0
	v_addc_co_u32_e32 v5, vcc, 0, v1, vcc
	global_load_dwordx4 v[40:43], v[4:5], off offset:1024
	global_load_dwordx4 v[36:39], v[4:5], off offset:2048
	global_load_dwordx4 v[32:35], v[4:5], off offset:3072
	global_load_dwordx4 v[28:31], v[2:3], off
	global_load_dwordx4 v[24:27], v[2:3], off offset:1024
	global_load_dwordx4 v[20:23], v[2:3], off offset:2048
	global_load_dwordx4 v[16:19], v[2:3], off offset:3072
	v_add_co_u32_e32 v0, vcc, s41, v0
	s_waitcnt vmcnt(11)
	v_mul_f32_e32 v67, v61, v61
	v_addc_co_u32_e32 v1, vcc, 0, v1, vcc
	global_load_dwordx4 v[12:15], v[0:1], off
	global_load_dwordx4 v[8:11], v[0:1], off offset:1024
	global_load_dwordx4 v[4:7], v[0:1], off offset:2048
	s_nop 0
	global_load_dwordx4 v[0:3], v[0:1], off offset:3072
	v_mul_f32_e32 v69, v63, v63
	s_waitcnt vmcnt(14)
	v_mul_f32_e32 v138, v57, v57
	v_mul_f32_e32 v139, v59, v59
	s_waitcnt vmcnt(13)
	v_mul_f32_e32 v145, v53, v53
	v_mul_f32_e32 v146, v55, v55
	v_fmac_f32_e32 v67, v60, v60
	v_fmac_f32_e32 v69, v62, v62
	v_fmac_f32_e32 v138, v56, v56
	v_fmac_f32_e32 v139, v58, v58
	s_waitcnt vmcnt(12)
	v_mul_f32_e32 v147, v49, v49
	v_mul_f32_e32 v148, v51, v51
	v_fmac_f32_e32 v145, v52, v52
	v_fmac_f32_e32 v146, v54, v54
	v_add_f32_e32 v67, v67, v69
	v_add_f32_e32 v69, v138, v139
	v_fmac_f32_e32 v147, v48, v48
	v_fmac_f32_e32 v148, v50, v50
	s_waitcnt vmcnt(11)
	v_mul_f32_e32 v149, v45, v45
	v_mul_f32_e32 v150, v47, v47
	v_add_f32_e32 v138, v145, v146
	v_add_f32_e32 v67, v67, v69
	s_waitcnt vmcnt(10)
	v_mul_f32_e32 v151, v41, v41
	v_mul_f32_e32 v152, v43, v43
	v_add_f32_e32 v139, v147, v148
	v_fmac_f32_e32 v149, v44, v44
	v_fmac_f32_e32 v150, v46, v46
	v_add_f32_e32 v67, v67, v138
	s_waitcnt vmcnt(9)
	v_mul_f32_e32 v153, v37, v37
	v_mul_f32_e32 v154, v39, v39
	v_fmac_f32_e32 v151, v40, v40
	v_fmac_f32_e32 v152, v42, v42
	v_add_f32_e32 v69, v149, v150
	v_add_f32_e32 v67, v67, v139
	s_waitcnt vmcnt(8)
	v_mul_f32_e32 v155, v33, v33
	v_mul_f32_e32 v156, v35, v35
	v_fmac_f32_e32 v153, v36, v36
	v_fmac_f32_e32 v154, v38, v38
	v_add_f32_e32 v145, v151, v152
	v_add_f32_e32 v67, v67, v69
	s_waitcnt vmcnt(7)
	v_mul_f32_e32 v157, v29, v29
	v_mul_f32_e32 v158, v31, v31
	v_fmac_f32_e32 v155, v32, v32
	v_fmac_f32_e32 v156, v34, v34
	v_add_f32_e32 v146, v153, v154
	v_add_f32_e32 v67, v67, v145
	s_waitcnt vmcnt(6)
	v_mul_f32_e32 v159, v25, v25
	v_mul_f32_e32 v160, v27, v27
	v_fmac_f32_e32 v157, v28, v28
	v_fmac_f32_e32 v158, v30, v30
	v_add_f32_e32 v147, v155, v156
	v_add_f32_e32 v67, v67, v146
	s_waitcnt vmcnt(5)
	v_mul_f32_e32 v161, v21, v21
	v_mul_f32_e32 v162, v23, v23
	v_fmac_f32_e32 v159, v24, v24
	v_fmac_f32_e32 v160, v26, v26
	v_add_f32_e32 v148, v157, v158
	v_add_f32_e32 v67, v67, v147
	v_fmac_f32_e32 v161, v20, v20
	v_fmac_f32_e32 v162, v22, v22
	v_add_f32_e32 v149, v159, v160
	v_add_f32_e32 v67, v67, v148
	s_waitcnt vmcnt(4)
	v_mul_f32_e32 v69, v17, v17
	v_mul_f32_e32 v138, v19, v19
	v_add_f32_e32 v150, v161, v162
	v_add_f32_e32 v67, v67, v149
	v_fmac_f32_e32 v69, v16, v16
	v_fmac_f32_e32 v138, v18, v18
	v_add_f32_e32 v67, v67, v150
	v_add_f32_e32 v69, v69, v138
	v_add_f32_e32 v67, v67, v69
	v_mov_b32_e32 v230, 0x1000
	v_mov_b32_e32 v231, 0
	v_lshl_add_u64 v[228:229], v[72:73], 0, v[230:231]
	v_lshl_add_u64 v[232:233], v[228:229], 0, v[230:231]
	v_lshl_add_u64 v[234:235], v[232:233], 0, v[230:231]
	global_load_dwordx4 v[164:167], v[72:73], off
	global_load_dwordx4 v[168:171], v[72:73], off offset:1024
	global_load_dwordx4 v[172:175], v[72:73], off offset:2048
	global_load_dwordx4 v[176:179], v[72:73], off offset:3072
	global_load_dwordx4 v[180:183], v[228:229], off
	global_load_dwordx4 v[184:187], v[228:229], off offset:1024
	global_load_dwordx4 v[188:191], v[228:229], off offset:2048
	global_load_dwordx4 v[192:195], v[228:229], off offset:3072
	global_load_dwordx4 v[196:199], v[232:233], off
	global_load_dwordx4 v[200:203], v[232:233], off offset:1024
	global_load_dwordx4 v[204:207], v[232:233], off offset:2048
	global_load_dwordx4 v[208:211], v[232:233], off offset:3072
	global_load_dwordx4 v[212:215], v[234:235], off
	global_load_dwordx4 v[216:219], v[234:235], off offset:1024
	global_load_dwordx4 v[220:223], v[234:235], off offset:2048
	global_load_dwordx4 v[224:227], v[234:235], off offset:3072
	s_waitcnt vmcnt(19)
	v_mul_f32_e32 v69, v13, v13
	v_mul_f32_e32 v138, v15, v15
	v_fmac_f32_e32 v69, v12, v12
	v_fmac_f32_e32 v138, v14, v14
	v_add_f32_e32 v69, v69, v138
	v_add_f32_e32 v67, v67, v69
	s_waitcnt vmcnt(18)
	v_mul_f32_e32 v69, v9, v9
	v_mul_f32_e32 v138, v11, v11
	v_fmac_f32_e32 v69, v8, v8
	v_fmac_f32_e32 v138, v10, v10
	v_add_f32_e32 v69, v69, v138
	v_add_f32_e32 v67, v67, v69
	s_waitcnt vmcnt(17)
	v_mul_f32_e32 v69, v5, v5
	v_mul_f32_e32 v138, v7, v7
	v_fmac_f32_e32 v69, v4, v4
	v_fmac_f32_e32 v138, v6, v6
	v_add_f32_e32 v69, v69, v138
	v_add_f32_e32 v67, v67, v69
	s_waitcnt vmcnt(16)
	v_mul_f32_e32 v69, v1, v1
	v_mul_f32_e32 v138, v3, v3
	v_fmac_f32_e32 v69, v0, v0
	v_fmac_f32_e32 v138, v2, v2
	v_add_f32_e32 v69, v69, v138
	v_add_f32_e32 v67, v67, v69
	v_and_b32_e32 v69, 64, v142
	v_add_u32_e32 v69, 64, v69
	v_xor_b32_e32 v138, 1, v142
	v_cmp_lt_i32_e32 vcc, v138, v69
	s_nop 1
	v_cndmask_b32_e32 v138, v142, v138, vcc
	v_lshlrev_b32_e32 v138, 2, v138
	ds_bpermute_b32 v138, v138, v67
	s_waitcnt lgkmcnt(0)
	v_add_f32_e32 v67, v67, v138
	v_xor_b32_e32 v138, 2, v142
	v_cmp_lt_i32_e32 vcc, v138, v69
	s_nop 1
	v_cndmask_b32_e32 v138, v142, v138, vcc
	v_lshlrev_b32_e32 v138, 2, v138
	ds_bpermute_b32 v138, v138, v67
	s_waitcnt lgkmcnt(0)
	v_add_f32_e32 v67, v67, v138
	v_xor_b32_e32 v138, 4, v142
	v_cmp_lt_i32_e32 vcc, v138, v69
	s_nop 1
	v_cndmask_b32_e32 v138, v142, v138, vcc
	v_lshlrev_b32_e32 v138, 2, v138
	ds_bpermute_b32 v138, v138, v67
	s_waitcnt lgkmcnt(0)
	v_add_f32_e32 v67, v67, v138
	v_xor_b32_e32 v138, 8, v142
	v_cmp_lt_i32_e32 vcc, v138, v69
	s_nop 1
	v_cndmask_b32_e32 v138, v142, v138, vcc
	v_lshlrev_b32_e32 v138, 2, v138
	ds_bpermute_b32 v138, v138, v67
	s_waitcnt lgkmcnt(0)
	v_add_f32_e32 v67, v67, v138
	v_xor_b32_e32 v138, 16, v142
	v_cmp_lt_i32_e32 vcc, v138, v69
	s_nop 1
	v_cndmask_b32_e32 v138, v142, v138, vcc
	v_lshlrev_b32_e32 v138, 2, v138
	ds_bpermute_b32 v138, v138, v67
	s_waitcnt lgkmcnt(0)
	v_add_f32_e32 v67, v67, v138
	v_xor_b32_e32 v138, 32, v142
	v_cmp_lt_i32_e32 vcc, v138, v69
	s_nop 1
	v_cndmask_b32_e32 v69, v142, v138, vcc
	v_lshlrev_b32_e32 v69, 2, v69
	ds_bpermute_b32 v69, v69, v67
	s_waitcnt lgkmcnt(0)
	v_add_f32_e32 v67, v67, v69
	v_fmamk_f32 v67, v67, 0x39800000, v140
	v_mul_f32_e32 v69, 0x4f800000, v67
	v_cmp_gt_f32_e32 vcc, s42, v67
	s_nop 1
	v_cndmask_b32_e32 v67, v67, v69, vcc
	v_sqrt_f32_e32 v69, v67
	s_nop 0
	v_add_u32_e32 v138, -1, v69
	v_fma_f32 v139, -v138, v69, v67
	v_cmp_ge_f32_e64 s[0:1], 0, v139
	v_add_u32_e32 v139, 1, v69
	s_nop 0
	v_cndmask_b32_e64 v138, v69, v138, s[0:1]
	v_fma_f32 v69, -v139, v69, v67
	v_cmp_lt_f32_e64 s[0:1], 0, v69
	s_nop 1
	v_cndmask_b32_e64 v69, v138, v139, s[0:1]
	v_mul_f32_e32 v138, 0x37800000, v69
	v_cndmask_b32_e32 v69, v69, v138, vcc
	v_cmp_class_f32_e32 vcc, v67, v141
	s_nop 1
	v_cndmask_b32_e32 v67, v69, v67, vcc
	v_div_scale_f32 v69, s[0:1], v67, v67, s43
	v_rcp_f32_e32 v138, v69
	s_lshr_b32 s0, s9, 3
	s_and_b32 s0, s0, 0xfe0
	v_fma_f32 v139, -v69, v138, 1.0
	v_fmac_f32_e32 v138, v139, v138
	v_div_scale_f32 v139, vcc, s43, v67, s43
	v_mul_f32_e32 v145, v139, v138
	v_fma_f32 v150, -v69, v145, v139
	v_fmac_f32_e32 v145, v150, v138
	v_fma_f32 v69, -v69, v145, v139
	v_div_fmas_f32 v69, v69, v138, v145
	v_div_fixup_f32 v67, v69, v67, s43
	v_add_u32_e32 v138, s0, v68
	v_mul_f32_e32 v60, v60, v67
	v_mul_f32_e32 v61, v61, v67
	v_mul_f32_e32 v62, v62, v67
	v_mul_f32_e32 v63, v63, v67
	v_ashrrev_i32_e32 v139, 31, v138
	s_waitcnt vmcnt(0)
	v_mul_f32_e32 v60, v164, v60
	v_mul_f32_e32 v61, v165, v61
	v_mul_f32_e32 v62, v166, v62
	v_mul_f32_e32 v63, v167, v63
	v_lshlrev_b64 v[138:139], 15, v[138:139]
	v_med3_f32 v60, v60, s44, v143
	v_med3_f32 v61, v61, s44, v143
	v_med3_f32 v62, v62, s44, v143
	v_med3_f32 v63, v63, s44, v143
	v_lshl_add_u64 v[138:139], s[12:13], 0, v[138:139]
	v_add_f32_e32 v60, 0x4b400000, v60
	v_add_f32_e32 v61, 0x4b400000, v61
	v_add_f32_e32 v62, 0x4b400000, v62
	v_add_f32_e32 v63, 0x4b400000, v63
	v_lshl_add_u64 v[138:139], v[138:139], 0, s[28:29]
	v_perm_b32 v60, v61, v60, s45
	v_perm_b32 v61, v63, v62, s45
	v_lshl_add_u64 v[138:139], v[138:139], 0, v[64:65]
	v_lshl_or_b32 v60, v61, 16, v60
	global_store_dword v[138:139], v60, off
	v_mul_f32_e32 v56, v56, v67
	v_mul_f32_e32 v57, v57, v67
	v_mul_f32_e32 v58, v58, v67
	v_mul_f32_e32 v59, v59, v67
	v_add_co_u32_e32 v146, vcc, s46, v138
	v_mul_f32_e32 v52, v52, v67
	s_nop 0
	v_addc_co_u32_e32 v147, vcc, 0, v139, vcc
	v_mul_f32_e32 v53, v53, v67
	v_mul_f32_e32 v54, v54, v67
	v_mul_f32_e32 v55, v55, v67
	v_mul_f32_e32 v48, v48, v67
	v_mul_f32_e32 v49, v49, v67
	v_mul_f32_e32 v50, v50, v67
	v_mul_f32_e32 v51, v51, v67
	v_mul_f32_e32 v44, v44, v67
	v_mul_f32_e32 v45, v45, v67
	v_mul_f32_e32 v46, v46, v67
	v_mul_f32_e32 v47, v47, v67
	v_mul_f32_e32 v40, v40, v67
	v_mul_f32_e32 v41, v41, v67
	v_mul_f32_e32 v42, v42, v67
	v_mul_f32_e32 v43, v43, v67
	v_mul_f32_e32 v36, v36, v67
	v_mul_f32_e32 v37, v37, v67
	v_mul_f32_e32 v38, v38, v67
	v_mul_f32_e32 v39, v39, v67
	v_mul_f32_e32 v32, v32, v67
	v_mul_f32_e32 v33, v33, v67
	v_mul_f32_e32 v34, v34, v67
	v_mul_f32_e32 v35, v35, v67
	v_mul_f32_e32 v28, v28, v67
	v_mul_f32_e32 v29, v29, v67
	v_mul_f32_e32 v30, v30, v67
	v_mul_f32_e32 v31, v31, v67
	v_mul_f32_e32 v24, v24, v67
	v_mul_f32_e32 v25, v25, v67
	v_mul_f32_e32 v26, v26, v67
	v_mul_f32_e32 v27, v27, v67
	v_mul_f32_e32 v20, v20, v67
	v_mul_f32_e32 v21, v21, v67
	v_mul_f32_e32 v22, v22, v67
	v_mul_f32_e32 v23, v23, v67
	v_mul_f32_e32 v16, v16, v67
	v_mul_f32_e32 v17, v17, v67
	v_mul_f32_e32 v18, v18, v67
	v_mul_f32_e32 v19, v19, v67
	v_mul_f32_e32 v12, v12, v67
	v_mul_f32_e32 v13, v13, v67
	v_mul_f32_e32 v14, v14, v67
	v_mul_f32_e32 v15, v15, v67
	v_mul_f32_e32 v8, v8, v67
	v_mul_f32_e32 v9, v9, v67
	v_mul_f32_e32 v10, v10, v67
	v_mul_f32_e32 v11, v11, v67
	v_mul_f32_e32 v4, v4, v67
	v_mul_f32_e32 v5, v5, v67
	v_mul_f32_e32 v6, v6, v67
	v_mul_f32_e32 v7, v7, v67
	v_mul_f32_e32 v0, v0, v67
	v_mul_f32_e32 v1, v1, v67
	v_mul_f32_e32 v2, v2, v67
	v_mul_f32_e32 v3, v3, v67
	v_mul_f32_e32 v56, v168, v56
	v_mul_f32_e32 v57, v169, v57
	v_mul_f32_e32 v58, v170, v58
	v_mul_f32_e32 v59, v171, v59
	v_med3_f32 v56, v56, s44, v143
	v_med3_f32 v57, v57, s44, v143
	v_med3_f32 v58, v58, s44, v143
	v_med3_f32 v59, v59, s44, v143
	v_add_f32_e32 v56, 0x4b400000, v56
	v_add_f32_e32 v57, 0x4b400000, v57
	v_add_f32_e32 v58, 0x4b400000, v58
	v_add_f32_e32 v59, 0x4b400000, v59
	v_perm_b32 v56, v57, v56, s45
	v_perm_b32 v57, v59, v58, s45
	v_lshl_or_b32 v56, v57, 16, v56
	global_store_dword v[146:147], v56, off
	v_add_co_u32_e32 v60, vcc, s47, v138
	v_mul_f32_e32 v52, v172, v52
	v_mul_f32_e32 v53, v173, v53
	v_mul_f32_e32 v54, v174, v54
	v_mul_f32_e32 v55, v175, v55
	v_med3_f32 v52, v52, s44, v143
	v_med3_f32 v53, v53, s44, v143
	v_med3_f32 v54, v54, s44, v143
	v_med3_f32 v55, v55, s44, v143
	v_add_f32_e32 v52, 0x4b400000, v52
	v_add_f32_e32 v53, 0x4b400000, v53
	v_add_f32_e32 v54, 0x4b400000, v54
	v_add_f32_e32 v55, 0x4b400000, v55
	v_perm_b32 v52, v53, v52, s45
	v_perm_b32 v53, v55, v54, s45
	v_addc_co_u32_e32 v61, vcc, 0, v139, vcc
	v_lshl_or_b32 v52, v53, 16, v52
	global_store_dword v[60:61], v52, off
	v_add_co_u32_e32 v56, vcc, s49, v138
	v_mul_f32_e32 v48, v176, v48
	v_mul_f32_e32 v49, v177, v49
	v_mul_f32_e32 v50, v178, v50
	v_mul_f32_e32 v51, v179, v51
	v_med3_f32 v48, v48, s44, v143
	v_med3_f32 v49, v49, s44, v143
	v_med3_f32 v50, v50, s44, v143
	v_med3_f32 v51, v51, s44, v143
	v_add_f32_e32 v48, 0x4b400000, v48
	v_add_f32_e32 v49, 0x4b400000, v49
	v_add_f32_e32 v50, 0x4b400000, v50
	v_add_f32_e32 v51, 0x4b400000, v51
	v_perm_b32 v48, v49, v48, s45
	v_perm_b32 v49, v51, v50, s45
	v_addc_co_u32_e32 v57, vcc, 0, v139, vcc
	v_lshl_or_b32 v48, v49, 16, v48
	global_store_dword v[56:57], v48, off
	v_add_co_u32_e32 v52, vcc, s50, v138
	v_mul_f32_e32 v44, v44, v180
	v_mul_f32_e32 v45, v45, v181
	v_mul_f32_e32 v46, v46, v182
	v_mul_f32_e32 v47, v47, v183
	v_med3_f32 v44, v44, s44, v143
	v_med3_f32 v45, v45, s44, v143
	v_med3_f32 v46, v46, s44, v143
	v_med3_f32 v47, v47, s44, v143
	v_add_f32_e32 v44, 0x4b400000, v44
	v_add_f32_e32 v45, 0x4b400000, v45
	v_add_f32_e32 v46, 0x4b400000, v46
	v_add_f32_e32 v47, 0x4b400000, v47
	v_perm_b32 v44, v45, v44, s45
	v_perm_b32 v45, v47, v46, s45
	v_addc_co_u32_e32 v53, vcc, 0, v139, vcc
	v_lshl_or_b32 v44, v45, 16, v44
	global_store_dword v[52:53], v44, off
	v_add_co_u32_e32 v48, vcc, s51, v138
	v_mul_f32_e32 v40, v40, v184
	v_mul_f32_e32 v41, v41, v185
	v_mul_f32_e32 v42, v42, v186
	v_mul_f32_e32 v43, v43, v187
	v_med3_f32 v40, v40, s44, v143
	v_med3_f32 v41, v41, s44, v143
	v_med3_f32 v42, v42, s44, v143
	v_med3_f32 v43, v43, s44, v143
	v_add_f32_e32 v40, 0x4b400000, v40
	v_add_f32_e32 v41, 0x4b400000, v41
	v_add_f32_e32 v42, 0x4b400000, v42
	v_add_f32_e32 v43, 0x4b400000, v43
	v_perm_b32 v40, v41, v40, s45
	v_perm_b32 v41, v43, v42, s45
	v_addc_co_u32_e32 v49, vcc, 0, v139, vcc
	v_lshl_or_b32 v40, v41, 16, v40
	global_store_dword v[48:49], v40, off
	v_add_co_u32_e32 v44, vcc, s52, v138
	v_mul_f32_e32 v36, v36, v188
	v_mul_f32_e32 v37, v37, v189
	v_mul_f32_e32 v38, v38, v190
	v_mul_f32_e32 v39, v39, v191
	v_med3_f32 v36, v36, s44, v143
	v_med3_f32 v37, v37, s44, v143
	v_med3_f32 v38, v38, s44, v143
	v_med3_f32 v39, v39, s44, v143
	v_add_f32_e32 v36, 0x4b400000, v36
	v_add_f32_e32 v37, 0x4b400000, v37
	v_add_f32_e32 v38, 0x4b400000, v38
	v_add_f32_e32 v39, 0x4b400000, v39
	v_perm_b32 v36, v37, v36, s45
	v_perm_b32 v37, v39, v38, s45
	v_addc_co_u32_e32 v45, vcc, 0, v139, vcc
	v_lshl_or_b32 v36, v37, 16, v36
	global_store_dword v[44:45], v36, off
	v_add_co_u32_e32 v40, vcc, s53, v138
	v_mul_f32_e32 v32, v32, v192
	v_mul_f32_e32 v33, v33, v193
	v_mul_f32_e32 v34, v34, v194
	v_mul_f32_e32 v35, v35, v195
	v_med3_f32 v32, v32, s44, v143
	v_med3_f32 v33, v33, s44, v143
	v_med3_f32 v34, v34, s44, v143
	v_med3_f32 v35, v35, s44, v143
	v_add_f32_e32 v32, 0x4b400000, v32
	v_add_f32_e32 v33, 0x4b400000, v33
	v_add_f32_e32 v34, 0x4b400000, v34
	v_add_f32_e32 v35, 0x4b400000, v35
	v_perm_b32 v32, v33, v32, s45
	v_perm_b32 v33, v35, v34, s45
	v_addc_co_u32_e32 v41, vcc, 0, v139, vcc
	v_lshl_or_b32 v32, v33, 16, v32
	global_store_dword v[40:41], v32, off
	v_add_co_u32_e32 v36, vcc, s54, v138
	v_mul_f32_e32 v28, v28, v196
	v_mul_f32_e32 v29, v29, v197
	v_mul_f32_e32 v30, v30, v198
	v_mul_f32_e32 v31, v31, v199
	v_med3_f32 v28, v28, s44, v143
	v_med3_f32 v29, v29, s44, v143
	v_med3_f32 v30, v30, s44, v143
	v_med3_f32 v31, v31, s44, v143
	v_add_f32_e32 v28, 0x4b400000, v28
	v_add_f32_e32 v29, 0x4b400000, v29
	v_add_f32_e32 v30, 0x4b400000, v30
	v_add_f32_e32 v31, 0x4b400000, v31
	v_perm_b32 v28, v29, v28, s45
	v_perm_b32 v29, v31, v30, s45
	v_addc_co_u32_e32 v37, vcc, 0, v139, vcc
	v_lshl_or_b32 v28, v29, 16, v28
	global_store_dword v[36:37], v28, off
	v_add_co_u32_e32 v32, vcc, s55, v138
	v_mul_f32_e32 v24, v24, v200
	v_mul_f32_e32 v25, v25, v201
	v_mul_f32_e32 v26, v26, v202
	v_mul_f32_e32 v27, v27, v203
	v_med3_f32 v24, v24, s44, v143
	v_med3_f32 v25, v25, s44, v143
	v_med3_f32 v26, v26, s44, v143
	v_med3_f32 v27, v27, s44, v143
	v_add_f32_e32 v24, 0x4b400000, v24
	v_add_f32_e32 v25, 0x4b400000, v25
	v_add_f32_e32 v26, 0x4b400000, v26
	v_add_f32_e32 v27, 0x4b400000, v27
	v_perm_b32 v24, v25, v24, s45
	v_perm_b32 v25, v27, v26, s45
	v_addc_co_u32_e32 v33, vcc, 0, v139, vcc
	v_lshl_or_b32 v24, v25, 16, v24
	global_store_dword v[32:33], v24, off
	v_add_co_u32_e32 v28, vcc, s56, v138
	v_mul_f32_e32 v20, v20, v204
	v_mul_f32_e32 v21, v21, v205
	v_mul_f32_e32 v22, v22, v206
	v_mul_f32_e32 v23, v23, v207
	v_med3_f32 v20, v20, s44, v143
	v_med3_f32 v21, v21, s44, v143
	v_med3_f32 v22, v22, s44, v143
	v_med3_f32 v23, v23, s44, v143
	v_add_f32_e32 v20, 0x4b400000, v20
	v_add_f32_e32 v21, 0x4b400000, v21
	v_add_f32_e32 v22, 0x4b400000, v22
	v_add_f32_e32 v23, 0x4b400000, v23
	v_perm_b32 v20, v21, v20, s45
	v_perm_b32 v21, v23, v22, s45
	v_addc_co_u32_e32 v29, vcc, 0, v139, vcc
	v_lshl_or_b32 v20, v21, 16, v20
	global_store_dword v[28:29], v20, off
	v_add_co_u32_e32 v24, vcc, s57, v138
	v_mul_f32_e32 v16, v16, v208
	v_mul_f32_e32 v17, v17, v209
	v_mul_f32_e32 v18, v18, v210
	v_mul_f32_e32 v19, v19, v211
	v_med3_f32 v16, v16, s44, v143
	v_med3_f32 v17, v17, s44, v143
	v_med3_f32 v18, v18, s44, v143
	v_med3_f32 v19, v19, s44, v143
	v_add_f32_e32 v16, 0x4b400000, v16
	v_add_f32_e32 v17, 0x4b400000, v17
	v_add_f32_e32 v18, 0x4b400000, v18
	v_add_f32_e32 v19, 0x4b400000, v19
	v_perm_b32 v16, v17, v16, s45
	v_perm_b32 v17, v19, v18, s45
	v_addc_co_u32_e32 v25, vcc, 0, v139, vcc
	v_lshl_or_b32 v16, v17, 16, v16
	global_store_dword v[24:25], v16, off
	v_add_co_u32_e32 v20, vcc, s58, v138
	v_mul_f32_e32 v12, v12, v212
	v_mul_f32_e32 v13, v13, v213
	v_mul_f32_e32 v14, v14, v214
	v_mul_f32_e32 v15, v15, v215
	v_med3_f32 v12, v12, s44, v143
	v_med3_f32 v13, v13, s44, v143
	v_med3_f32 v14, v14, s44, v143
	v_med3_f32 v15, v15, s44, v143
	v_add_f32_e32 v12, 0x4b400000, v12
	v_add_f32_e32 v13, 0x4b400000, v13
	v_add_f32_e32 v14, 0x4b400000, v14
	v_add_f32_e32 v15, 0x4b400000, v15
	v_perm_b32 v12, v13, v12, s45
	v_perm_b32 v13, v15, v14, s45
	v_addc_co_u32_e32 v21, vcc, 0, v139, vcc
	v_lshl_or_b32 v12, v13, 16, v12
	global_store_dword v[20:21], v12, off
	v_add_co_u32_e32 v16, vcc, s59, v138
	v_mul_f32_e32 v8, v8, v216
	v_mul_f32_e32 v9, v9, v217
	v_mul_f32_e32 v10, v10, v218
	v_mul_f32_e32 v11, v11, v219
	v_med3_f32 v8, v8, s44, v143
	v_med3_f32 v9, v9, s44, v143
	v_med3_f32 v10, v10, s44, v143
	v_med3_f32 v11, v11, s44, v143
	v_add_f32_e32 v8, 0x4b400000, v8
	v_add_f32_e32 v9, 0x4b400000, v9
	v_add_f32_e32 v10, 0x4b400000, v10
	v_add_f32_e32 v11, 0x4b400000, v11
	v_perm_b32 v8, v9, v8, s45
	v_perm_b32 v9, v11, v10, s45
	v_addc_co_u32_e32 v17, vcc, 0, v139, vcc
	v_lshl_or_b32 v8, v9, 16, v8
	global_store_dword v[16:17], v8, off
	v_add_co_u32_e32 v12, vcc, s60, v138
	v_mul_f32_e32 v4, v4, v220
	v_mul_f32_e32 v5, v5, v221
	v_mul_f32_e32 v6, v6, v222
	v_mul_f32_e32 v7, v7, v223
	v_med3_f32 v4, v4, s44, v143
	v_med3_f32 v5, v5, s44, v143
	v_med3_f32 v6, v6, s44, v143
	v_med3_f32 v7, v7, s44, v143
	v_add_f32_e32 v4, 0x4b400000, v4
	v_add_f32_e32 v5, 0x4b400000, v5
	v_add_f32_e32 v6, 0x4b400000, v6
	v_add_f32_e32 v7, 0x4b400000, v7
	v_perm_b32 v4, v5, v4, s45
	v_perm_b32 v5, v7, v6, s45
	v_addc_co_u32_e32 v13, vcc, 0, v139, vcc
	v_lshl_or_b32 v4, v5, 16, v4
	global_store_dword v[12:13], v4, off
	v_mul_f32_e32 v0, v0, v224
	v_mul_f32_e32 v1, v1, v225
	v_mul_f32_e32 v2, v2, v226
	v_mul_f32_e32 v3, v3, v227
	v_med3_f32 v0, v0, s44, v143
	v_med3_f32 v1, v1, s44, v143
	v_med3_f32 v2, v2, s44, v143
	v_med3_f32 v3, v3, s44, v143
	v_add_f32_e32 v0, 0x4b400000, v0
	v_add_f32_e32 v1, 0x4b400000, v1
	v_add_f32_e32 v2, 0x4b400000, v2
	v_add_f32_e32 v3, 0x4b400000, v3
	v_perm_b32 v0, v1, v0, s45
	v_perm_b32 v1, v3, v2, s45
	v_lshl_or_b32 v2, v1, 16, v0
	v_lshl_add_u64 v[0:1], v[138:139], 0, s[34:35]

.LBB0_29:
	s_andn2_b64 vcc, exec, s[0:1]
	s_cbranch_vccnz .LBB0_18
	v_add_co_u32_e32 v0, vcc, s40, v130
	global_load_dwordx4 v[60:63], v[130:131], off
	global_load_dwordx4 v[56:59], v[130:131], off offset:1024
	global_load_dwordx4 v[52:55], v[130:131], off offset:2048
	global_load_dwordx4 v[48:51], v[130:131], off offset:3072
	v_addc_co_u32_e32 v1, vcc, 0, v131, vcc
	global_load_dwordx4 v[44:47], v[0:1], off offset:-4096
	v_add_co_u32_e32 v2, vcc, s7, v130
	s_and_b32 s28, s3, 0x7f80
	s_nop 0
	v_addc_co_u32_e32 v3, vcc, 0, v131, vcc
	global_load_dwordx4 v[40:43], v[2:3], off offset:1024
	global_load_dwordx4 v[36:39], v[2:3], off offset:2048
	global_load_dwordx4 v[24:27], v[2:3], off offset:3072
	global_load_dwordx4 v[28:31], v[0:1], off
	global_load_dwordx4 v[32:35], v[0:1], off offset:1024
	global_load_dwordx4 v[20:23], v[0:1], off offset:2048
	global_load_dwordx4 v[16:19], v[0:1], off offset:3072
	v_add_co_u32_e32 v4, vcc, s41, v130
	s_waitcnt vmcnt(11)
	v_mul_f32_e32 v67, v61, v61
	v_addc_co_u32_e32 v5, vcc, 0, v131, vcc
	global_load_dwordx4 v[12:15], v[4:5], off
	global_load_dwordx4 v[8:11], v[4:5], off offset:1024
	global_load_dwordx4 v[0:3], v[4:5], off offset:3072
	s_nop 0
	global_load_dwordx4 v[4:7], v[4:5], off offset:2048
	v_mul_f32_e32 v69, v63, v63
	s_waitcnt vmcnt(14)
	v_mul_f32_e32 v138, v57, v57
	v_mul_f32_e32 v139, v59, v59
	s_waitcnt vmcnt(13)
	v_mul_f32_e32 v145, v53, v53
	v_mul_f32_e32 v146, v55, v55
	v_fmac_f32_e32 v67, v60, v60
	v_fmac_f32_e32 v69, v62, v62
	v_fmac_f32_e32 v138, v56, v56
	v_fmac_f32_e32 v139, v58, v58
	s_waitcnt vmcnt(12)
	v_mul_f32_e32 v147, v49, v49
	v_mul_f32_e32 v148, v51, v51
	v_fmac_f32_e32 v145, v52, v52
	v_fmac_f32_e32 v146, v54, v54
	v_add_f32_e32 v67, v67, v69
	v_add_f32_e32 v138, v138, v139
	v_fmac_f32_e32 v147, v48, v48
	v_fmac_f32_e32 v148, v50, v50
	s_waitcnt vmcnt(11)
	v_mul_f32_e32 v69, v45, v45
	v_mul_f32_e32 v139, v47, v47
	v_add_f32_e32 v145, v145, v146
	v_add_f32_e32 v67, v67, v138
	s_waitcnt vmcnt(10)
	v_mul_f32_e32 v146, v41, v41
	v_add_f32_e32 v147, v147, v148
	v_mul_f32_e32 v148, v43, v43
	v_fmac_f32_e32 v69, v44, v44
	v_fmac_f32_e32 v139, v46, v46
	v_add_f32_e32 v67, v67, v145
	s_waitcnt vmcnt(9)
	v_mul_f32_e32 v149, v37, v37
	v_mul_f32_e32 v150, v39, v39
	v_fmac_f32_e32 v146, v40, v40
	v_fmac_f32_e32 v148, v42, v42
	v_add_f32_e32 v69, v69, v139
	v_add_f32_e32 v67, v67, v147
	s_waitcnt vmcnt(8)
	v_mul_f32_e32 v151, v25, v25
	v_mul_f32_e32 v152, v27, v27
	v_fmac_f32_e32 v149, v36, v36
	v_fmac_f32_e32 v150, v38, v38
	v_add_f32_e32 v138, v146, v148
	v_add_f32_e32 v67, v67, v69
	s_waitcnt vmcnt(7)
	v_mul_f32_e32 v153, v29, v29
	v_mul_f32_e32 v154, v31, v31
	v_fmac_f32_e32 v151, v24, v24
	v_fmac_f32_e32 v152, v26, v26
	v_add_f32_e32 v139, v149, v150
	v_add_f32_e32 v67, v67, v138
	s_waitcnt vmcnt(6)
	v_mul_f32_e32 v155, v33, v33
	v_mul_f32_e32 v156, v35, v35
	v_fmac_f32_e32 v153, v28, v28
	v_fmac_f32_e32 v154, v30, v30
	v_add_f32_e32 v146, v151, v152
	v_add_f32_e32 v67, v67, v139
	s_waitcnt vmcnt(5)
	v_mul_f32_e32 v157, v21, v21
	v_mul_f32_e32 v158, v23, v23
	v_fmac_f32_e32 v155, v32, v32
	v_fmac_f32_e32 v156, v34, v34
	v_add_f32_e32 v148, v153, v154
	v_add_f32_e32 v67, v67, v146
	v_fmac_f32_e32 v157, v20, v20
	v_fmac_f32_e32 v158, v22, v22
	v_add_f32_e32 v149, v155, v156
	v_add_f32_e32 v67, v67, v148
	s_waitcnt vmcnt(4)
	v_mul_f32_e32 v69, v17, v17
	v_mul_f32_e32 v138, v19, v19
	v_add_f32_e32 v150, v157, v158
	v_add_f32_e32 v67, v67, v149
	v_fmac_f32_e32 v69, v16, v16
	v_fmac_f32_e32 v138, v18, v18
	v_add_f32_e32 v67, v67, v150
	v_add_f32_e32 v69, v69, v138
	v_add_f32_e32 v67, v67, v69
	v_mov_b32_e32 v230, 0x1000
	v_mov_b32_e32 v231, 0
	v_lshl_add_u64 v[228:229], v[72:73], 0, v[230:231]
	v_lshl_add_u64 v[232:233], v[228:229], 0, v[230:231]
	v_lshl_add_u64 v[234:235], v[232:233], 0, v[230:231]
	global_load_dwordx4 v[164:167], v[72:73], off
	global_load_dwordx4 v[168:171], v[72:73], off offset:1024
	global_load_dwordx4 v[172:175], v[72:73], off offset:2048
	global_load_dwordx4 v[176:179], v[72:73], off offset:3072
	global_load_dwordx4 v[180:183], v[228:229], off
	global_load_dwordx4 v[184:187], v[228:229], off offset:1024
	global_load_dwordx4 v[188:191], v[228:229], off offset:2048
	global_load_dwordx4 v[192:195], v[228:229], off offset:3072
	global_load_dwordx4 v[196:199], v[232:233], off
	global_load_dwordx4 v[200:203], v[232:233], off offset:1024
	global_load_dwordx4 v[204:207], v[232:233], off offset:2048
	global_load_dwordx4 v[208:211], v[232:233], off offset:3072
	global_load_dwordx4 v[212:215], v[234:235], off
	global_load_dwordx4 v[216:219], v[234:235], off offset:1024
	global_load_dwordx4 v[220:223], v[234:235], off offset:2048
	global_load_dwordx4 v[224:227], v[234:235], off offset:3072
	s_waitcnt vmcnt(19)
	v_mul_f32_e32 v69, v13, v13
	v_mul_f32_e32 v138, v15, v15
	v_fmac_f32_e32 v69, v12, v12
	v_fmac_f32_e32 v138, v14, v14
	v_add_f32_e32 v69, v69, v138
	v_add_f32_e32 v67, v67, v69
	s_waitcnt vmcnt(18)
	v_mul_f32_e32 v69, v9, v9
	v_mul_f32_e32 v138, v11, v11
	v_fmac_f32_e32 v69, v8, v8
	v_fmac_f32_e32 v138, v10, v10
	v_add_f32_e32 v69, v69, v138
	v_add_f32_e32 v67, v67, v69
	s_waitcnt vmcnt(16)
	v_mul_f32_e32 v69, v5, v5
	v_mul_f32_e32 v138, v7, v7
	v_fmac_f32_e32 v69, v4, v4
	v_fmac_f32_e32 v138, v6, v6
	v_add_f32_e32 v69, v69, v138
	v_add_f32_e32 v67, v67, v69
	v_mul_f32_e32 v69, v1, v1
	v_mul_f32_e32 v138, v3, v3
	v_fmac_f32_e32 v69, v0, v0
	v_fmac_f32_e32 v138, v2, v2
	v_add_f32_e32 v69, v69, v138
	v_add_f32_e32 v67, v67, v69
	v_and_b32_e32 v69, 64, v142
	v_add_u32_e32 v69, 64, v69
	v_xor_b32_e32 v138, 1, v142
	v_cmp_lt_i32_e32 vcc, v138, v69
	s_nop 1
	v_cndmask_b32_e32 v138, v142, v138, vcc
	v_lshlrev_b32_e32 v138, 2, v138
	ds_bpermute_b32 v138, v138, v67
	s_waitcnt lgkmcnt(0)
	v_add_f32_e32 v67, v67, v138
	v_xor_b32_e32 v138, 2, v142
	v_cmp_lt_i32_e32 vcc, v138, v69
	s_nop 1
	v_cndmask_b32_e32 v138, v142, v138, vcc
	v_lshlrev_b32_e32 v138, 2, v138
	ds_bpermute_b32 v138, v138, v67
	s_waitcnt lgkmcnt(0)
	v_add_f32_e32 v67, v67, v138
	v_xor_b32_e32 v138, 4, v142
	v_cmp_lt_i32_e32 vcc, v138, v69
	s_nop 1
	v_cndmask_b32_e32 v138, v142, v138, vcc
	v_lshlrev_b32_e32 v138, 2, v138
	ds_bpermute_b32 v138, v138, v67
	s_waitcnt lgkmcnt(0)
	v_add_f32_e32 v67, v67, v138
	v_xor_b32_e32 v138, 8, v142
	v_cmp_lt_i32_e32 vcc, v138, v69
	s_nop 1
	v_cndmask_b32_e32 v138, v142, v138, vcc
	v_lshlrev_b32_e32 v138, 2, v138
	ds_bpermute_b32 v138, v138, v67
	s_waitcnt lgkmcnt(0)
	v_add_f32_e32 v67, v67, v138
	v_xor_b32_e32 v138, 16, v142
	v_cmp_lt_i32_e32 vcc, v138, v69
	s_nop 1
	v_cndmask_b32_e32 v138, v142, v138, vcc
	v_lshlrev_b32_e32 v138, 2, v138
	ds_bpermute_b32 v138, v138, v67
	s_waitcnt lgkmcnt(0)
	v_add_f32_e32 v67, v67, v138
	v_xor_b32_e32 v138, 32, v142
	v_cmp_lt_i32_e32 vcc, v138, v69
	s_nop 1
	v_cndmask_b32_e32 v69, v142, v138, vcc
	v_lshlrev_b32_e32 v69, 2, v69
	ds_bpermute_b32 v69, v69, v67
	s_waitcnt lgkmcnt(0)
	v_add_f32_e32 v67, v67, v69
	v_fmamk_f32 v67, v67, 0x39800000, v140
	v_mul_f32_e32 v69, 0x4f800000, v67
	v_cmp_gt_f32_e32 vcc, s42, v67
	s_nop 1
	v_cndmask_b32_e32 v67, v67, v69, vcc
	v_sqrt_f32_e32 v69, v67
	s_nop 0
	v_add_u32_e32 v138, -1, v69
	v_fma_f32 v139, -v138, v69, v67
	v_cmp_ge_f32_e64 s[0:1], 0, v139
	v_add_u32_e32 v139, 1, v69
	s_nop 0
	v_cndmask_b32_e64 v138, v69, v138, s[0:1]
	v_fma_f32 v69, -v139, v69, v67
	v_cmp_lt_f32_e64 s[0:1], 0, v69
	s_nop 1
	v_cndmask_b32_e64 v69, v138, v139, s[0:1]
	v_mul_f32_e32 v138, 0x37800000, v69
	v_cndmask_b32_e32 v69, v69, v138, vcc
	v_cmp_class_f32_e32 vcc, v67, v141
	s_nop 1
	v_cndmask_b32_e32 v67, v69, v67, vcc
	v_div_scale_f32 v69, s[0:1], v67, v67, s43
	v_rcp_f32_e32 v138, v69
	s_ashr_i32 s0, s9, 3
	s_andn2_b32 s0, s0, 31
	v_fma_f32 v139, -v69, v138, 1.0
	v_fmac_f32_e32 v138, v139, v138
	v_div_scale_f32 v139, vcc, s43, v67, s43
	v_mul_f32_e32 v145, v139, v138
	v_fma_f32 v150, -v69, v145, v139
	v_fmac_f32_e32 v145, v150, v138
	v_fma_f32 v69, -v69, v145, v139
	v_div_fmas_f32 v69, v69, v138, v145
	v_div_fixup_f32 v67, v69, v67, s43
	v_mul_f32_e32 v60, v60, v67
	v_mul_f32_e32 v61, v61, v67
	s_waitcnt vmcnt(0)
	v_mul_f32_e32 v60, v164, v60
	v_mul_f32_e32 v61, v165, v61
	v_mul_f32_e32 v62, v62, v67
	v_mul_f32_e32 v63, v63, v67
	v_med3_f32 v60, v60, s44, v143
	v_med3_f32 v61, v61, s44, v143
	v_mul_f32_e32 v62, v166, v62
	v_mul_f32_e32 v63, v167, v63
	v_add_f32_e32 v60, 0x4b400000, v60
	v_add_f32_e32 v61, 0x4b400000, v61
	v_perm_b32 v60, v61, v60, s45
	v_med3_f32 v61, v62, s44, v143
	v_med3_f32 v62, v63, s44, v143
	v_add_f32_e32 v61, 0x4b400000, v61
	v_add_f32_e32 v62, 0x4b400000, v62
	v_perm_b32 v61, v62, v61, s45
	v_lshl_or_b32 v62, v61, 16, v60
	v_add_u32_e32 v60, s0, v68
	v_ashrrev_i32_e32 v61, 31, v60
	v_lshlrev_b64 v[60:61], 15, v[60:61]
	v_lshl_add_u64 v[60:61], s[12:13], 0, v[60:61]
	v_lshl_add_u64 v[60:61], v[60:61], 0, s[28:29]
	v_lshl_add_u64 v[60:61], v[60:61], 0, v[64:65]
	global_store_dword v[60:61], v62, off
	v_mul_f32_e32 v56, v56, v67
	v_mul_f32_e32 v57, v57, v67
	v_mul_f32_e32 v58, v58, v67
	v_mul_f32_e32 v59, v59, v67
	v_add_co_u32_e32 v62, vcc, s46, v60
	v_mul_f32_e32 v52, v52, v67
	s_nop 0
	v_addc_co_u32_e32 v63, vcc, 0, v61, vcc
	v_mul_f32_e32 v53, v53, v67
	v_mul_f32_e32 v54, v54, v67
	v_mul_f32_e32 v55, v55, v67
	v_mul_f32_e32 v48, v48, v67
	v_mul_f32_e32 v49, v49, v67
	v_mul_f32_e32 v50, v50, v67
	v_mul_f32_e32 v51, v51, v67
	v_mul_f32_e32 v44, v44, v67
	v_mul_f32_e32 v45, v45, v67
	v_mul_f32_e32 v46, v46, v67
	v_mul_f32_e32 v47, v47, v67
	v_mul_f32_e32 v40, v40, v67
	v_mul_f32_e32 v41, v41, v67
	v_mul_f32_e32 v42, v42, v67
	v_mul_f32_e32 v43, v43, v67
	v_mul_f32_e32 v36, v36, v67
	v_mul_f32_e32 v37, v37, v67
	v_mul_f32_e32 v38, v38, v67
	v_mul_f32_e32 v39, v39, v67
	v_mul_f32_e32 v24, v24, v67
	v_mul_f32_e32 v25, v25, v67
	v_mul_f32_e32 v26, v26, v67
	v_mul_f32_e32 v27, v27, v67
	v_mul_f32_e32 v28, v28, v67
	v_mul_f32_e32 v29, v29, v67
	v_mul_f32_e32 v30, v30, v67
	v_mul_f32_e32 v31, v31, v67
	v_mul_f32_e32 v20, v20, v67
	v_mul_f32_e32 v21, v21, v67
	v_mul_f32_e32 v22, v22, v67
	v_mul_f32_e32 v23, v23, v67
	v_mul_f32_e32 v16, v16, v67
	v_mul_f32_e32 v17, v17, v67
	v_mul_f32_e32 v18, v18, v67
	v_mul_f32_e32 v19, v19, v67
	v_mul_f32_e32 v12, v12, v67
	v_mul_f32_e32 v13, v13, v67
	v_mul_f32_e32 v14, v14, v67
	v_mul_f32_e32 v15, v15, v67
	v_mul_f32_e32 v8, v8, v67
	v_mul_f32_e32 v9, v9, v67
	v_mul_f32_e32 v10, v10, v67
	v_mul_f32_e32 v11, v11, v67
	v_mul_f32_e32 v4, v4, v67
	v_mul_f32_e32 v5, v5, v67
	v_mul_f32_e32 v6, v6, v67
	v_mul_f32_e32 v7, v7, v67
	v_mul_f32_e32 v0, v0, v67
	v_mul_f32_e32 v1, v1, v67
	v_mul_f32_e32 v2, v2, v67
	v_mul_f32_e32 v3, v3, v67
	v_mul_f32_e32 v56, v168, v56
	v_mul_f32_e32 v57, v169, v57
	v_mul_f32_e32 v58, v170, v58
	v_mul_f32_e32 v59, v171, v59
	v_med3_f32 v56, v56, s44, v143
	v_med3_f32 v57, v57, s44, v143
	v_med3_f32 v58, v58, s44, v143
	v_med3_f32 v59, v59, s44, v143
	v_add_f32_e32 v56, 0x4b400000, v56
	v_add_f32_e32 v57, 0x4b400000, v57
	v_add_f32_e32 v58, 0x4b400000, v58
	v_add_f32_e32 v59, 0x4b400000, v59
	v_perm_b32 v56, v57, v56, s45
	v_perm_b32 v57, v59, v58, s45
	v_lshl_or_b32 v56, v57, 16, v56
	global_store_dword v[62:63], v56, off
	v_add_co_u32_e32 v62, vcc, s47, v60
	v_mul_f32_e32 v52, v172, v52
	v_mul_f32_e32 v53, v173, v53
	v_mul_f32_e32 v54, v174, v54
	v_mul_f32_e32 v55, v175, v55
	v_med3_f32 v52, v52, s44, v143
	v_med3_f32 v53, v53, s44, v143
	v_med3_f32 v54, v54, s44, v143
	v_med3_f32 v55, v55, s44, v143
	v_add_f32_e32 v52, 0x4b400000, v52
	v_add_f32_e32 v53, 0x4b400000, v53
	v_add_f32_e32 v54, 0x4b400000, v54
	v_add_f32_e32 v55, 0x4b400000, v55
	v_perm_b32 v52, v53, v52, s45
	v_perm_b32 v53, v55, v54, s45
	v_addc_co_u32_e32 v63, vcc, 0, v61, vcc
	v_lshl_or_b32 v52, v53, 16, v52
	global_store_dword v[62:63], v52, off
	v_add_co_u32_e32 v56, vcc, s49, v60
	v_mul_f32_e32 v48, v176, v48
	v_mul_f32_e32 v49, v177, v49
	v_mul_f32_e32 v50, v178, v50
	v_mul_f32_e32 v51, v179, v51
	v_med3_f32 v48, v48, s44, v143
	v_med3_f32 v49, v49, s44, v143
	v_med3_f32 v50, v50, s44, v143
	v_med3_f32 v51, v51, s44, v143
	v_add_f32_e32 v48, 0x4b400000, v48
	v_add_f32_e32 v49, 0x4b400000, v49
	v_add_f32_e32 v50, 0x4b400000, v50
	v_add_f32_e32 v51, 0x4b400000, v51
	v_perm_b32 v48, v49, v48, s45
	v_perm_b32 v49, v51, v50, s45
	v_addc_co_u32_e32 v57, vcc, 0, v61, vcc
	v_lshl_or_b32 v48, v49, 16, v48
	global_store_dword v[56:57], v48, off
	v_add_co_u32_e32 v52, vcc, s50, v60
	v_mul_f32_e32 v44, v44, v180
	v_mul_f32_e32 v45, v45, v181
	v_mul_f32_e32 v46, v46, v182
	v_mul_f32_e32 v47, v47, v183
	v_med3_f32 v44, v44, s44, v143
	v_med3_f32 v45, v45, s44, v143
	v_med3_f32 v46, v46, s44, v143
	v_med3_f32 v47, v47, s44, v143
	v_add_f32_e32 v44, 0x4b400000, v44
	v_add_f32_e32 v45, 0x4b400000, v45
	v_add_f32_e32 v46, 0x4b400000, v46
	v_add_f32_e32 v47, 0x4b400000, v47
	v_perm_b32 v44, v45, v44, s45
	v_perm_b32 v45, v47, v46, s45
	v_addc_co_u32_e32 v53, vcc, 0, v61, vcc
	v_lshl_or_b32 v44, v45, 16, v44
	global_store_dword v[52:53], v44, off
	v_add_co_u32_e32 v48, vcc, s51, v60
	v_mul_f32_e32 v40, v40, v184
	v_mul_f32_e32 v41, v41, v185
	v_mul_f32_e32 v42, v42, v186
	v_mul_f32_e32 v43, v43, v187
	v_med3_f32 v40, v40, s44, v143
	v_med3_f32 v41, v41, s44, v143
	v_med3_f32 v42, v42, s44, v143
	v_med3_f32 v43, v43, s44, v143
	v_add_f32_e32 v40, 0x4b400000, v40
	v_add_f32_e32 v41, 0x4b400000, v41
	v_add_f32_e32 v42, 0x4b400000, v42
	v_add_f32_e32 v43, 0x4b400000, v43
	v_perm_b32 v40, v41, v40, s45
	v_perm_b32 v41, v43, v42, s45
	v_addc_co_u32_e32 v49, vcc, 0, v61, vcc
	v_lshl_or_b32 v40, v41, 16, v40
	global_store_dword v[48:49], v40, off
	v_add_co_u32_e32 v44, vcc, s52, v60
	v_mul_f32_e32 v36, v36, v188
	v_mul_f32_e32 v37, v37, v189
	v_mul_f32_e32 v38, v38, v190
	v_mul_f32_e32 v39, v39, v191
	v_med3_f32 v36, v36, s44, v143
	v_med3_f32 v37, v37, s44, v143
	v_med3_f32 v38, v38, s44, v143
	v_med3_f32 v39, v39, s44, v143
	v_add_f32_e32 v36, 0x4b400000, v36
	v_add_f32_e32 v37, 0x4b400000, v37
	v_add_f32_e32 v38, 0x4b400000, v38
	v_add_f32_e32 v39, 0x4b400000, v39
	v_perm_b32 v36, v37, v36, s45
	v_perm_b32 v37, v39, v38, s45
	v_addc_co_u32_e32 v45, vcc, 0, v61, vcc
	v_lshl_or_b32 v36, v37, 16, v36
	global_store_dword v[44:45], v36, off
	v_add_co_u32_e32 v40, vcc, s53, v60
	v_mul_f32_e32 v24, v24, v192
	v_mul_f32_e32 v25, v25, v193
	v_mul_f32_e32 v26, v26, v194
	v_mul_f32_e32 v27, v27, v195
	v_med3_f32 v24, v24, s44, v143
	v_med3_f32 v25, v25, s44, v143
	v_med3_f32 v26, v26, s44, v143
	v_med3_f32 v27, v27, s44, v143
	v_add_f32_e32 v24, 0x4b400000, v24
	v_add_f32_e32 v25, 0x4b400000, v25
	v_add_f32_e32 v26, 0x4b400000, v26
	v_add_f32_e32 v27, 0x4b400000, v27
	v_perm_b32 v24, v25, v24, s45
	v_perm_b32 v25, v27, v26, s45
	v_addc_co_u32_e32 v41, vcc, 0, v61, vcc
	v_lshl_or_b32 v24, v25, 16, v24
	global_store_dword v[40:41], v24, off
	v_add_co_u32_e32 v36, vcc, s54, v60
	v_mul_f32_e32 v24, v28, v196
	v_mul_f32_e32 v25, v29, v197
	v_mul_f32_e32 v26, v30, v198
	v_mul_f32_e32 v27, v31, v199
	v_med3_f32 v24, v24, s44, v143
	v_med3_f32 v25, v25, s44, v143
	v_med3_f32 v26, v26, s44, v143
	v_med3_f32 v27, v27, s44, v143
	v_add_f32_e32 v24, 0x4b400000, v24
	v_add_f32_e32 v25, 0x4b400000, v25
	v_add_f32_e32 v26, 0x4b400000, v26
	v_add_f32_e32 v27, 0x4b400000, v27
	v_perm_b32 v24, v25, v24, s45
	v_perm_b32 v25, v27, v26, s45
	v_addc_co_u32_e32 v37, vcc, 0, v61, vcc
	v_lshl_or_b32 v24, v25, 16, v24
	global_store_dword v[36:37], v24, off
	v_mul_f32_e32 v30, v32, v67
	v_mul_f32_e32 v31, v33, v67
	v_mul_f32_e32 v32, v34, v67
	v_mul_f32_e32 v33, v35, v67
	v_add_co_u32_e32 v28, vcc, s55, v60
	v_mul_f32_e32 v24, v30, v200
	v_mul_f32_e32 v25, v31, v201
	v_mul_f32_e32 v26, v32, v202
	v_mul_f32_e32 v27, v33, v203
	v_med3_f32 v24, v24, s44, v143
	v_med3_f32 v25, v25, s44, v143
	v_med3_f32 v26, v26, s44, v143
	v_med3_f32 v27, v27, s44, v143
	v_add_f32_e32 v24, 0x4b400000, v24
	v_add_f32_e32 v25, 0x4b400000, v25
	v_add_f32_e32 v26, 0x4b400000, v26
	v_add_f32_e32 v27, 0x4b400000, v27
	v_perm_b32 v24, v25, v24, s45
	v_perm_b32 v25, v27, v26, s45
	v_addc_co_u32_e32 v29, vcc, 0, v61, vcc
	v_lshl_or_b32 v24, v25, 16, v24
	global_store_dword v[28:29], v24, off
	v_add_co_u32_e32 v28, vcc, s56, v60
	v_mul_f32_e32 v20, v20, v204
	v_mul_f32_e32 v21, v21, v205
	v_mul_f32_e32 v22, v22, v206
	v_mul_f32_e32 v23, v23, v207
	v_med3_f32 v20, v20, s44, v143
	v_med3_f32 v21, v21, s44, v143
	v_med3_f32 v22, v22, s44, v143
	v_med3_f32 v23, v23, s44, v143
	v_add_f32_e32 v20, 0x4b400000, v20
	v_add_f32_e32 v21, 0x4b400000, v21
	v_add_f32_e32 v22, 0x4b400000, v22
	v_add_f32_e32 v23, 0x4b400000, v23
	v_perm_b32 v20, v21, v20, s45
	v_perm_b32 v21, v23, v22, s45
	v_addc_co_u32_e32 v29, vcc, 0, v61, vcc
	v_lshl_or_b32 v20, v21, 16, v20
	global_store_dword v[28:29], v20, off
	v_add_co_u32_e32 v24, vcc, s57, v60
	v_mul_f32_e32 v16, v16, v208
	v_mul_f32_e32 v17, v17, v209
	v_mul_f32_e32 v18, v18, v210
	v_mul_f32_e32 v19, v19, v211
	v_med3_f32 v16, v16, s44, v143
	v_med3_f32 v17, v17, s44, v143
	v_med3_f32 v18, v18, s44, v143
	v_med3_f32 v19, v19, s44, v143
	v_add_f32_e32 v16, 0x4b400000, v16
	v_add_f32_e32 v17, 0x4b400000, v17
	v_add_f32_e32 v18, 0x4b400000, v18
	v_add_f32_e32 v19, 0x4b400000, v19
	v_perm_b32 v16, v17, v16, s45
	v_perm_b32 v17, v19, v18, s45
	v_addc_co_u32_e32 v25, vcc, 0, v61, vcc
	v_lshl_or_b32 v16, v17, 16, v16
	global_store_dword v[24:25], v16, off
	v_add_co_u32_e32 v20, vcc, s58, v60
	v_mul_f32_e32 v12, v12, v212
	v_mul_f32_e32 v13, v13, v213
	v_mul_f32_e32 v14, v14, v214
	v_mul_f32_e32 v15, v15, v215
	v_med3_f32 v12, v12, s44, v143
	v_med3_f32 v13, v13, s44, v143
	v_med3_f32 v14, v14, s44, v143
	v_med3_f32 v15, v15, s44, v143
	v_add_f32_e32 v12, 0x4b400000, v12
	v_add_f32_e32 v13, 0x4b400000, v13
	v_add_f32_e32 v14, 0x4b400000, v14
	v_add_f32_e32 v15, 0x4b400000, v15
	v_perm_b32 v12, v13, v12, s45
	v_perm_b32 v13, v15, v14, s45
	v_addc_co_u32_e32 v21, vcc, 0, v61, vcc
	v_lshl_or_b32 v12, v13, 16, v12
	global_store_dword v[20:21], v12, off
	v_add_co_u32_e32 v16, vcc, s59, v60
	v_mul_f32_e32 v8, v8, v216
	v_mul_f32_e32 v9, v9, v217
	v_mul_f32_e32 v10, v10, v218
	v_mul_f32_e32 v11, v11, v219
	v_med3_f32 v8, v8, s44, v143
	v_med3_f32 v9, v9, s44, v143
	v_med3_f32 v10, v10, s44, v143
	v_med3_f32 v11, v11, s44, v143
	v_add_f32_e32 v8, 0x4b400000, v8
	v_add_f32_e32 v9, 0x4b400000, v9
	v_add_f32_e32 v10, 0x4b400000, v10
	v_add_f32_e32 v11, 0x4b400000, v11
	v_perm_b32 v8, v9, v8, s45
	v_perm_b32 v9, v11, v10, s45
	v_addc_co_u32_e32 v17, vcc, 0, v61, vcc
	v_lshl_or_b32 v8, v9, 16, v8
	global_store_dword v[16:17], v8, off
	v_add_co_u32_e32 v12, vcc, s60, v60
	v_mul_f32_e32 v4, v4, v220
	v_mul_f32_e32 v5, v5, v221
	v_mul_f32_e32 v6, v6, v222
	v_mul_f32_e32 v7, v7, v223
	v_med3_f32 v4, v4, s44, v143
	v_med3_f32 v5, v5, s44, v143
	v_med3_f32 v6, v6, s44, v143
	v_med3_f32 v7, v7, s44, v143
	v_add_f32_e32 v4, 0x4b400000, v4
	v_add_f32_e32 v5, 0x4b400000, v5
	v_add_f32_e32 v6, 0x4b400000, v6
	v_add_f32_e32 v7, 0x4b400000, v7
	v_perm_b32 v4, v5, v4, s45
	v_perm_b32 v5, v7, v6, s45
	v_addc_co_u32_e32 v13, vcc, 0, v61, vcc
	v_lshl_or_b32 v4, v5, 16, v4
	global_store_dword v[12:13], v4, off
	v_mul_f32_e32 v0, v0, v224
	v_mul_f32_e32 v1, v1, v225
	v_mul_f32_e32 v2, v2, v226
	v_mul_f32_e32 v3, v3, v227
	v_med3_f32 v0, v0, s44, v143
	v_med3_f32 v1, v1, s44, v143
	v_med3_f32 v2, v2, s44, v143
	v_med3_f32 v3, v3, s44, v143
	v_add_f32_e32 v0, 0x4b400000, v0
	v_add_f32_e32 v1, 0x4b400000, v1
	v_add_f32_e32 v2, 0x4b400000, v2
	v_add_f32_e32 v3, 0x4b400000, v3
	v_perm_b32 v0, v1, v0, s45
	v_perm_b32 v1, v3, v2, s45
	v_lshl_or_b32 v2, v1, 16, v0
	v_lshl_add_u64 v[0:1], v[60:61], 0, s[34:35]
	s_branch .LBB0_18

.LBB0_47:
	s_lshl_b32 s68, s66, 1
	s_lshl_b32 s69, s33, 1
	v_add_u32_e32 v6, s69, v9
	v_add_u32_e32 v7, s68, v10
	v_add_u32_e32 v2, s28, v6
	v_add_u32_e32 v4, s9, v7
	v_ashrrev_i32_e32 v5, 31, v4
	v_ashrrev_i32_e32 v3, 31, v2
	v_lshlrev_b64 v[2:3], 14, v[2:3]
	v_lshlrev_b64 v[4:5], 14, v[4:5]
	v_lshl_add_u64 v[4:5], v[0:1], 0, v[4:5]
	v_lshl_add_u64 v[2:3], v[0:1], 0, v[2:3]
	global_load_dword v163, v[4:5], off
	s_nop 0
	global_load_dword v164, v[2:3], off
	v_and_b32_e32 v3, 28, v6
	v_and_b32_e32 v5, 28, v7
	v_xor_b32_e32 v3, v3, v11
	v_xor_b32_e32 v5, v5, v12
	v_lshlrev_b32_e32 v6, 7, v6
	v_lshlrev_b32_e32 v7, 7, v7
	v_lshlrev_b32_e32 v5, 2, v5
	v_lshlrev_b32_e32 v3, 2, v3
	v_add3_u32 v195, s37, v7, v5
	v_add3_u32 v196, s37, v6, v3
	v_add_u32_e32 v6, s69, v13
	v_add_u32_e32 v7, s68, v14
	s_add_i32 s66, s66, 32
	s_add_i32 s33, s33, 32
	s_sub_i32 s67, s67, 32
	s_cmp_lg_u32 s67, 0
	v_add_u32_e32 v2, s28, v6
	v_add_u32_e32 v4, s9, v7
	v_ashrrev_i32_e32 v5, 31, v4
	v_ashrrev_i32_e32 v3, 31, v2
	v_lshlrev_b64 v[2:3], 14, v[2:3]
	v_lshlrev_b64 v[4:5], 14, v[4:5]
	v_lshl_add_u64 v[4:5], v[0:1], 0, v[4:5]
	v_lshl_add_u64 v[2:3], v[0:1], 0, v[2:3]
	global_load_dword v165, v[4:5], off
	s_nop 0
	global_load_dword v166, v[2:3], off
	v_and_b32_e32 v3, 28, v6
	v_and_b32_e32 v5, 28, v7
	v_xor_b32_e32 v3, v3, v11
	v_xor_b32_e32 v5, v5, v12
	v_lshlrev_b32_e32 v6, 7, v6
	v_lshlrev_b32_e32 v7, 7, v7
	v_lshlrev_b32_e32 v5, 2, v5
	v_lshlrev_b32_e32 v3, 2, v3
	v_add3_u32 v197, s37, v7, v5
	v_add3_u32 v198, s37, v6, v3
	v_add_u32_e32 v6, s69, v15
	v_add_u32_e32 v7, s68, v16
	v_add_u32_e32 v2, s28, v6
	v_add_u32_e32 v4, s9, v7
	v_ashrrev_i32_e32 v5, 31, v4
	v_ashrrev_i32_e32 v3, 31, v2
	v_lshlrev_b64 v[2:3], 14, v[2:3]
	v_lshlrev_b64 v[4:5], 14, v[4:5]
	v_lshl_add_u64 v[4:5], v[0:1], 0, v[4:5]
	v_lshl_add_u64 v[2:3], v[0:1], 0, v[2:3]
	global_load_dword v167, v[4:5], off
	s_nop 0
	global_load_dword v168, v[2:3], off
	v_and_b32_e32 v3, 28, v6
	v_and_b32_e32 v5, 28, v7
	v_xor_b32_e32 v3, v3, v11
	v_xor_b32_e32 v5, v5, v12
	v_lshlrev_b32_e32 v6, 7, v6
	v_lshlrev_b32_e32 v7, 7, v7
	v_lshlrev_b32_e32 v5, 2, v5
	v_lshlrev_b32_e32 v3, 2, v3
	v_add3_u32 v199, s37, v7, v5
	v_add3_u32 v200, s37, v6, v3
	v_add_u32_e32 v6, s69, v17
	v_add_u32_e32 v7, s68, v18
	v_add_u32_e32 v2, s28, v6
	v_add_u32_e32 v4, s9, v7
	v_ashrrev_i32_e32 v5, 31, v4
	v_ashrrev_i32_e32 v3, 31, v2
	v_lshlrev_b64 v[2:3], 14, v[2:3]
	v_lshlrev_b64 v[4:5], 14, v[4:5]
	v_lshl_add_u64 v[4:5], v[0:1], 0, v[4:5]
	v_lshl_add_u64 v[2:3], v[0:1], 0, v[2:3]
	global_load_dword v169, v[4:5], off
	s_nop 0
	global_load_dword v170, v[2:3], off
	v_and_b32_e32 v3, 28, v6
	v_and_b32_e32 v5, 28, v7
	v_xor_b32_e32 v3, v3, v11
	v_xor_b32_e32 v5, v5, v12
	v_lshlrev_b32_e32 v6, 7, v6
	v_lshlrev_b32_e32 v7, 7, v7
	v_lshlrev_b32_e32 v5, 2, v5
	v_lshlrev_b32_e32 v3, 2, v3
	v_add3_u32 v201, s37, v7, v5
	v_add3_u32 v202, s37, v6, v3
	v_add_u32_e32 v6, s69, v19
	v_add_u32_e32 v7, s68, v20
	v_add_u32_e32 v2, s28, v6
	v_add_u32_e32 v4, s9, v7
	v_ashrrev_i32_e32 v5, 31, v4
	v_ashrrev_i32_e32 v3, 31, v2
	v_lshlrev_b64 v[2:3], 14, v[2:3]
	v_lshlrev_b64 v[4:5], 14, v[4:5]
	v_lshl_add_u64 v[4:5], v[0:1], 0, v[4:5]
	v_lshl_add_u64 v[2:3], v[0:1], 0, v[2:3]
	global_load_dword v171, v[4:5], off
	s_nop 0
	global_load_dword v172, v[2:3], off
	v_and_b32_e32 v3, 28, v6
	v_and_b32_e32 v5, 28, v7
	v_xor_b32_e32 v3, v3, v11
	v_xor_b32_e32 v5, v5, v12
	v_lshlrev_b32_e32 v6, 7, v6
	v_lshlrev_b32_e32 v7, 7, v7
	v_lshlrev_b32_e32 v5, 2, v5
	v_lshlrev_b32_e32 v3, 2, v3
	v_add3_u32 v203, s37, v7, v5
	v_add3_u32 v204, s37, v6, v3
	v_add_u32_e32 v6, s69, v21
	v_add_u32_e32 v7, s68, v22
	v_add_u32_e32 v2, s28, v6
	v_add_u32_e32 v4, s9, v7
	v_ashrrev_i32_e32 v5, 31, v4
	v_ashrrev_i32_e32 v3, 31, v2
	v_lshlrev_b64 v[2:3], 14, v[2:3]
	v_lshlrev_b64 v[4:5], 14, v[4:5]
	v_lshl_add_u64 v[4:5], v[0:1], 0, v[4:5]
	v_lshl_add_u64 v[2:3], v[0:1], 0, v[2:3]
	global_load_dword v173, v[4:5], off
	s_nop 0
	global_load_dword v174, v[2:3], off
	v_and_b32_e32 v3, 28, v6
	v_and_b32_e32 v5, 28, v7
	v_xor_b32_e32 v3, v3, v11
	v_xor_b32_e32 v5, v5, v12
	v_lshlrev_b32_e32 v6, 7, v6
	v_lshlrev_b32_e32 v7, 7, v7
	v_lshlrev_b32_e32 v5, 2, v5
	v_lshlrev_b32_e32 v3, 2, v3
	v_add3_u32 v205, s37, v7, v5
	v_add3_u32 v206, s37, v6, v3
	v_add_u32_e32 v6, s69, v23
	v_add_u32_e32 v7, s68, v24
	v_add_u32_e32 v2, s28, v6
	v_add_u32_e32 v4, s9, v7
	v_ashrrev_i32_e32 v5, 31, v4
	v_ashrrev_i32_e32 v3, 31, v2
	v_lshlrev_b64 v[2:3], 14, v[2:3]
	v_lshlrev_b64 v[4:5], 14, v[4:5]
	v_lshl_add_u64 v[4:5], v[0:1], 0, v[4:5]
	v_lshl_add_u64 v[2:3], v[0:1], 0, v[2:3]
	global_load_dword v175, v[4:5], off
	s_nop 0
	global_load_dword v176, v[2:3], off
	v_and_b32_e32 v3, 28, v6
	v_and_b32_e32 v5, 28, v7
	v_xor_b32_e32 v3, v3, v11
	v_xor_b32_e32 v5, v5, v12
	v_lshlrev_b32_e32 v6, 7, v6
	v_lshlrev_b32_e32 v7, 7, v7
	v_lshlrev_b32_e32 v5, 2, v5
	v_lshlrev_b32_e32 v3, 2, v3
	v_add3_u32 v207, s37, v7, v5
	v_add3_u32 v208, s37, v6, v3
	v_add_u32_e32 v6, s69, v25
	v_add_u32_e32 v7, s68, v26
	v_add_u32_e32 v2, s28, v6
	v_add_u32_e32 v4, s9, v7
	v_ashrrev_i32_e32 v5, 31, v4
	v_ashrrev_i32_e32 v3, 31, v2
	v_lshlrev_b64 v[2:3], 14, v[2:3]
	v_lshlrev_b64 v[4:5], 14, v[4:5]
	v_lshl_add_u64 v[4:5], v[0:1], 0, v[4:5]
	v_lshl_add_u64 v[2:3], v[0:1], 0, v[2:3]
	global_load_dword v177, v[4:5], off
	s_nop 0
	global_load_dword v178, v[2:3], off
	v_and_b32_e32 v3, 28, v6
	v_and_b32_e32 v5, 28, v7
	v_xor_b32_e32 v3, v3, v11
	v_xor_b32_e32 v5, v5, v12
	v_lshlrev_b32_e32 v6, 7, v6
	v_lshlrev_b32_e32 v7, 7, v7
	v_lshlrev_b32_e32 v5, 2, v5
	v_lshlrev_b32_e32 v3, 2, v3
	v_add3_u32 v209, s37, v7, v5
	v_add3_u32 v210, s37, v6, v3
	v_add_u32_e32 v6, s69, v27
	v_add_u32_e32 v7, s68, v28
	v_add_u32_e32 v2, s28, v6
	v_add_u32_e32 v4, s9, v7
	v_ashrrev_i32_e32 v5, 31, v4
	v_ashrrev_i32_e32 v3, 31, v2
	v_lshlrev_b64 v[2:3], 14, v[2:3]
	v_lshlrev_b64 v[4:5], 14, v[4:5]
	v_lshl_add_u64 v[4:5], v[0:1], 0, v[4:5]
	v_lshl_add_u64 v[2:3], v[0:1], 0, v[2:3]
	global_load_dword v179, v[4:5], off
	s_nop 0
	global_load_dword v180, v[2:3], off
	v_and_b32_e32 v3, 28, v6
	v_and_b32_e32 v5, 28, v7
	v_xor_b32_e32 v3, v3, v11
	v_xor_b32_e32 v5, v5, v12
	v_lshlrev_b32_e32 v6, 7, v6
	v_lshlrev_b32_e32 v7, 7, v7
	v_lshlrev_b32_e32 v5, 2, v5
	v_lshlrev_b32_e32 v3, 2, v3
	v_add3_u32 v211, s37, v7, v5
	v_add3_u32 v212, s37, v6, v3
	v_add_u32_e32 v6, s69, v29
	v_add_u32_e32 v7, s68, v30
	v_add_u32_e32 v2, s28, v6
	v_add_u32_e32 v4, s9, v7
	v_ashrrev_i32_e32 v5, 31, v4
	v_ashrrev_i32_e32 v3, 31, v2
	v_lshlrev_b64 v[2:3], 14, v[2:3]
	v_lshlrev_b64 v[4:5], 14, v[4:5]
	v_lshl_add_u64 v[4:5], v[0:1], 0, v[4:5]
	v_lshl_add_u64 v[2:3], v[0:1], 0, v[2:3]
	global_load_dword v181, v[4:5], off
	s_nop 0
	global_load_dword v182, v[2:3], off
	v_and_b32_e32 v3, 28, v6
	v_and_b32_e32 v5, 28, v7
	v_xor_b32_e32 v3, v3, v11
	v_xor_b32_e32 v5, v5, v12
	v_lshlrev_b32_e32 v6, 7, v6
	v_lshlrev_b32_e32 v7, 7, v7
	v_lshlrev_b32_e32 v5, 2, v5
	v_lshlrev_b32_e32 v3, 2, v3
	v_add3_u32 v213, s37, v7, v5
	v_add3_u32 v214, s37, v6, v3
	v_add_u32_e32 v6, s69, v31
	v_add_u32_e32 v7, s68, v32
	v_add_u32_e32 v2, s28, v6
	v_add_u32_e32 v4, s9, v7
	v_ashrrev_i32_e32 v5, 31, v4
	v_ashrrev_i32_e32 v3, 31, v2
	v_lshlrev_b64 v[2:3], 14, v[2:3]
	v_lshlrev_b64 v[4:5], 14, v[4:5]
	v_lshl_add_u64 v[4:5], v[0:1], 0, v[4:5]
	v_lshl_add_u64 v[2:3], v[0:1], 0, v[2:3]
	global_load_dword v183, v[4:5], off
	s_nop 0
	global_load_dword v184, v[2:3], off
	v_and_b32_e32 v3, 28, v6
	v_and_b32_e32 v5, 28, v7
	v_xor_b32_e32 v3, v3, v11
	v_xor_b32_e32 v5, v5, v12
	v_lshlrev_b32_e32 v6, 7, v6
	v_lshlrev_b32_e32 v7, 7, v7
	v_lshlrev_b32_e32 v5, 2, v5
	v_lshlrev_b32_e32 v3, 2, v3
	v_add3_u32 v215, s37, v7, v5
	v_add3_u32 v216, s37, v6, v3
	v_add_u32_e32 v6, s69, v33
	v_add_u32_e32 v7, s68, v34
	v_add_u32_e32 v2, s28, v6
	v_add_u32_e32 v4, s9, v7
	v_ashrrev_i32_e32 v5, 31, v4
	v_ashrrev_i32_e32 v3, 31, v2
	v_lshlrev_b64 v[2:3], 14, v[2:3]
	v_lshlrev_b64 v[4:5], 14, v[4:5]
	v_lshl_add_u64 v[4:5], v[0:1], 0, v[4:5]
	v_lshl_add_u64 v[2:3], v[0:1], 0, v[2:3]
	global_load_dword v185, v[4:5], off
	s_nop 0
	global_load_dword v186, v[2:3], off
	v_and_b32_e32 v3, 28, v6
	v_and_b32_e32 v5, 28, v7
	v_xor_b32_e32 v3, v3, v11
	v_xor_b32_e32 v5, v5, v12
	v_lshlrev_b32_e32 v6, 7, v6
	v_lshlrev_b32_e32 v7, 7, v7
	v_lshlrev_b32_e32 v5, 2, v5
	v_lshlrev_b32_e32 v3, 2, v3
	v_add3_u32 v217, s37, v7, v5
	v_add3_u32 v218, s37, v6, v3
	v_add_u32_e32 v6, s69, v35
	v_add_u32_e32 v7, s68, v36
	v_add_u32_e32 v2, s28, v6
	v_add_u32_e32 v4, s9, v7
	v_ashrrev_i32_e32 v5, 31, v4
	v_ashrrev_i32_e32 v3, 31, v2
	v_lshlrev_b64 v[2:3], 14, v[2:3]
	v_lshlrev_b64 v[4:5], 14, v[4:5]
	v_lshl_add_u64 v[4:5], v[0:1], 0, v[4:5]
	v_lshl_add_u64 v[2:3], v[0:1], 0, v[2:3]
	global_load_dword v187, v[4:5], off
	s_nop 0
	global_load_dword v188, v[2:3], off
	v_and_b32_e32 v3, 28, v6
	v_and_b32_e32 v5, 28, v7
	v_xor_b32_e32 v3, v3, v11
	v_xor_b32_e32 v5, v5, v12
	v_lshlrev_b32_e32 v6, 7, v6
	v_lshlrev_b32_e32 v7, 7, v7
	v_lshlrev_b32_e32 v5, 2, v5
	v_lshlrev_b32_e32 v3, 2, v3
	v_add3_u32 v219, s37, v7, v5
	v_add3_u32 v220, s37, v6, v3
	v_add_u32_e32 v6, s69, v37
	v_add_u32_e32 v7, s68, v38
	v_add_u32_e32 v2, s28, v6
	v_add_u32_e32 v4, s9, v7
	v_ashrrev_i32_e32 v5, 31, v4
	v_ashrrev_i32_e32 v3, 31, v2
	v_lshlrev_b64 v[2:3], 14, v[2:3]
	v_lshlrev_b64 v[4:5], 14, v[4:5]
	v_lshl_add_u64 v[4:5], v[0:1], 0, v[4:5]
	v_lshl_add_u64 v[2:3], v[0:1], 0, v[2:3]
	global_load_dword v189, v[4:5], off
	s_nop 0
	global_load_dword v190, v[2:3], off
	v_and_b32_e32 v3, 28, v6
	v_and_b32_e32 v5, 28, v7
	v_xor_b32_e32 v3, v3, v11
	v_xor_b32_e32 v5, v5, v12
	v_lshlrev_b32_e32 v6, 7, v6
	v_lshlrev_b32_e32 v7, 7, v7
	v_lshlrev_b32_e32 v5, 2, v5
	v_lshlrev_b32_e32 v3, 2, v3
	v_add3_u32 v221, s37, v7, v5
	v_add3_u32 v222, s37, v6, v3
	v_add_u32_e32 v6, s69, v39
	v_add_u32_e32 v7, s68, v40
	v_add_u32_e32 v2, s28, v6
	v_add_u32_e32 v4, s9, v7
	v_ashrrev_i32_e32 v5, 31, v4
	v_ashrrev_i32_e32 v3, 31, v2
	v_lshlrev_b64 v[2:3], 14, v[2:3]
	v_lshlrev_b64 v[4:5], 14, v[4:5]
	v_lshl_add_u64 v[4:5], v[0:1], 0, v[4:5]
	v_lshl_add_u64 v[2:3], v[0:1], 0, v[2:3]
	global_load_dword v191, v[4:5], off
	s_nop 0
	global_load_dword v192, v[2:3], off
	v_and_b32_e32 v3, 28, v6
	v_and_b32_e32 v5, 28, v7
	v_xor_b32_e32 v3, v3, v11
	v_xor_b32_e32 v5, v5, v12
	v_lshlrev_b32_e32 v6, 7, v6
	v_lshlrev_b32_e32 v7, 7, v7
	v_lshlrev_b32_e32 v5, 2, v5
	v_lshlrev_b32_e32 v3, 2, v3
	v_add3_u32 v223, s37, v7, v5
	v_add3_u32 v224, s37, v6, v3
	v_add_u32_e32 v6, s69, v41
	v_add_u32_e32 v7, s68, v42
	v_add_u32_e32 v2, s28, v6
	v_add_u32_e32 v4, s9, v7
	v_ashrrev_i32_e32 v5, 31, v4
	v_ashrrev_i32_e32 v3, 31, v2
	v_lshlrev_b64 v[2:3], 14, v[2:3]
	v_lshlrev_b64 v[4:5], 14, v[4:5]
	v_lshl_add_u64 v[4:5], v[0:1], 0, v[4:5]
	v_lshl_add_u64 v[2:3], v[0:1], 0, v[2:3]
	global_load_dword v193, v[4:5], off
	s_nop 0
	global_load_dword v194, v[2:3], off
	v_and_b32_e32 v5, 28, v7
	v_and_b32_e32 v3, 28, v6
	v_xor_b32_e32 v5, v5, v12
	v_xor_b32_e32 v3, v3, v11
	v_lshlrev_b32_e32 v7, 7, v7
	v_lshlrev_b32_e32 v5, 2, v5
	v_lshlrev_b32_e32 v6, 7, v6
	v_add3_u32 v225, s37, v7, v5
	v_lshlrev_b32_e32 v3, 2, v3
	v_add3_u32 v226, s37, v6, v3
	s_waitcnt vmcnt(0)
	ds_write_b32 v195, v163
	ds_write_b32 v196, v164
	ds_write_b32 v197, v165
	ds_write_b32 v198, v166
	ds_write_b32 v199, v167
	ds_write_b32 v200, v168
	ds_write_b32 v201, v169
	ds_write_b32 v202, v170
	ds_write_b32 v203, v171
	ds_write_b32 v204, v172
	ds_write_b32 v205, v173
	ds_write_b32 v206, v174
	ds_write_b32 v207, v175
	ds_write_b32 v208, v176
	ds_write_b32 v209, v177
	ds_write_b32 v210, v178
	ds_write_b32 v211, v179
	ds_write_b32 v212, v180
	ds_write_b32 v213, v181
	ds_write_b32 v214, v182
	ds_write_b32 v215, v183
	ds_write_b32 v216, v184
	ds_write_b32 v217, v185
	ds_write_b32 v218, v186
	ds_write_b32 v219, v187
	ds_write_b32 v220, v188
	ds_write_b32 v221, v189
	ds_write_b32 v222, v190
	ds_write_b32 v223, v191
	ds_write_b32 v224, v192
	ds_write_b32 v225, v193
	ds_write_b32 v226, v194
	s_cbranch_scc1 .LBB0_47
	s_waitcnt lgkmcnt(0)
	v_add_u32_e32 v56, v85, v84
	v_add_u32_e32 v57, 0x1000, v56
	ds_read2_b32 v[0:1], v56 offset1:32
	ds_read2_b32 v[2:3], v57 offset1:32
	v_add_u32_e32 v58, 0x2000, v56
	v_add_u32_e32 v59, 0x3000, v56
	ds_read2_b32 v[4:5], v58 offset1:32
	ds_read2_b32 v[6:7], v59 offset1:32
	s_waitcnt lgkmcnt(3)
	v_mul_f32_e32 v0, 0x45000000, v0
	s_waitcnt lgkmcnt(2)
	v_mul_f32_e32 v2, 0x45000000, v2
	v_med3_f32 v64, v0, s63, v144
	v_med3_f32 v2, v2, s63, v144
	v_mov_b32_e32 v0, v65
	v_cvt_pk_fp8_f32 v0, v64, v2
	s_waitcnt lgkmcnt(1)
	v_mul_f32_e32 v4, 0x45000000, v4
	s_waitcnt lgkmcnt(0)
	v_mul_f32_e32 v2, 0x45000000, v6
	v_med3_f32 v4, v4, s63, v144
	v_med3_f32 v2, v2, s63, v144
	v_cvt_pk_fp8_f32 v0, v4, v2 op_sel:[0,0,1]
	v_mul_f32_e32 v1, 0x45000000, v1
	v_mul_f32_e32 v2, 0x45000000, v3
	v_med3_f32 v4, v1, s63, v144
	v_med3_f32 v2, v2, s63, v144
	v_mov_b32_e32 v1, v65
	v_mul_f32_e32 v3, 0x45000000, v5
	v_cvt_pk_fp8_f32 v1, v4, v2
	v_mul_f32_e32 v64, 0x45000000, v7
	v_med3_f32 v92, v3, s63, v144
	ds_read2_b32 v[2:3], v56 offset0:64 offset1:96
	ds_read2_b32 v[4:5], v57 offset0:64 offset1:96
	ds_read2_b32 v[6:7], v58 offset0:64 offset1:96
	v_med3_f32 v56, v64, s63, v144
	v_cvt_pk_fp8_f32 v1, v92, v56 op_sel:[0,0,1]
	ds_read2_b32 v[56:57], v59 offset0:64 offset1:96
	s_waitcnt lgkmcnt(3)
	v_mul_f32_e32 v2, 0x45000000, v2
	s_waitcnt lgkmcnt(2)
	v_mul_f32_e32 v4, 0x45000000, v4
	v_med3_f32 v58, v2, s63, v144
	v_med3_f32 v4, v4, s63, v144
	v_mov_b32_e32 v2, v65
	v_cvt_pk_fp8_f32 v2, v58, v4
	s_waitcnt lgkmcnt(1)
	v_mul_f32_e32 v6, 0x45000000, v6
	s_waitcnt lgkmcnt(0)
	v_mul_f32_e32 v4, 0x45000000, v56
	v_med3_f32 v6, v6, s63, v144
	v_med3_f32 v4, v4, s63, v144
	v_cvt_pk_fp8_f32 v2, v6, v4 op_sel:[0,0,1]
	v_mul_f32_e32 v3, 0x45000000, v3
	v_mul_f32_e32 v4, 0x45000000, v5
	v_med3_f32 v6, v3, s63, v144
	v_med3_f32 v4, v4, s63, v144
	v_mov_b32_e32 v3, v65
	v_cvt_pk_fp8_f32 v3, v6, v4
	v_mul_f32_e32 v5, 0x45000000, v7
	v_mul_f32_e32 v4, 0x45000000, v57
	v_med3_f32 v5, v5, s63, v144
	v_med3_f32 v4, v4, s63, v144
	v_add_u32_e32 v6, s0, v66
	v_cvt_pk_fp8_f32 v3, v5, v4 op_sel:[0,0,1]
	v_ashrrev_i32_e32 v4, 3, v6
	s_lshr_b32 s1, s1, 7
	v_and_b32_e32 v4, 0xffffffe0, v4
	v_or_b32_e32 v4, s1, v4
	v_ashrrev_i32_e32 v5, 31, v4
	v_lshlrev_b64 v[4:5], 15, v[4:5]
	v_lshlrev_b32_e32 v6, 7, v6
	v_and_b32_e32 v64, 0x7f80, v6
	v_lshl_add_u64 v[4:5], s[22:23], 0, v[4:5]
	v_lshl_add_u64 v[4:5], v[4:5], 0, v[64:65]
	v_add_u32_e32 v64, v86, v84
	v_add_u32_e32 v92, 0x1000, v64
	ds_read2_b32 v[56:57], v92 offset1:32
	ds_read2_b32 v[6:7], v64 offset1:32
	v_lshl_add_u64 v[4:5], v[4:5], 0, v[44:45]
	v_add_u32_e32 v93, 0x2000, v64
	global_store_dwordx4 v[4:5], v[0:3], off
	ds_read2_b32 v[58:59], v93 offset1:32
	s_waitcnt lgkmcnt(0)
	v_mul_f32_e32 v4, 0x45000000, v58
	v_mul_f32_e32 v1, 0x45000000, v56
	v_add_u32_e32 v56, 0x3000, v64
	ds_read2_b32 v[2:3], v56 offset1:32
	v_mul_f32_e32 v0, 0x45000000, v6
	v_med3_f32 v5, v0, s63, v144
	v_med3_f32 v1, v1, s63, v144
	v_mov_b32_e32 v0, v65
	v_cvt_pk_fp8_f32 v0, v5, v1
	s_waitcnt lgkmcnt(0)
	v_mul_f32_e32 v1, 0x45000000, v2
	v_med3_f32 v2, v4, s63, v144
	v_med3_f32 v1, v1, s63, v144
	v_cvt_pk_fp8_f32 v0, v2, v1 op_sel:[0,0,1]
	v_mul_f32_e32 v1, 0x45000000, v7
	v_mul_f32_e32 v2, 0x45000000, v57
	v_mul_f32_e32 v57, 0x45000000, v3
	v_med3_f32 v3, v1, s63, v144
	v_med3_f32 v2, v2, s63, v144
	v_mov_b32_e32 v1, v65
	v_mul_f32_e32 v4, 0x45000000, v59
	v_cvt_pk_fp8_f32 v1, v3, v2
	v_med3_f32 v58, v4, s63, v144
	ds_read2_b32 v[2:3], v64 offset0:64 offset1:96
	ds_read2_b32 v[4:5], v92 offset0:64 offset1:96
	ds_read2_b32 v[6:7], v93 offset0:64 offset1:96
	v_med3_f32 v57, v57, s63, v144
	v_cvt_pk_fp8_f32 v1, v58, v57 op_sel:[0,0,1]
	ds_read2_b32 v[56:57], v56 offset0:64 offset1:96
	s_waitcnt lgkmcnt(3)
	v_mul_f32_e32 v2, 0x45000000, v2
	s_waitcnt lgkmcnt(2)
	v_mul_f32_e32 v4, 0x45000000, v4
	v_med3_f32 v58, v2, s63, v144
	v_med3_f32 v4, v4, s63, v144
	v_mov_b32_e32 v2, v65
	v_cvt_pk_fp8_f32 v2, v58, v4
	s_waitcnt lgkmcnt(1)
	v_mul_f32_e32 v6, 0x45000000, v6
	s_waitcnt lgkmcnt(0)
	v_mul_f32_e32 v4, 0x45000000, v56
	v_med3_f32 v6, v6, s63, v144
	v_med3_f32 v4, v4, s63, v144
	v_cvt_pk_fp8_f32 v2, v6, v4 op_sel:[0,0,1]
	v_mul_f32_e32 v3, 0x45000000, v3
	v_mul_f32_e32 v4, 0x45000000, v5
	v_med3_f32 v6, v3, s63, v144
	v_med3_f32 v4, v4, s63, v144
	v_mov_b32_e32 v3, v65
	v_cvt_pk_fp8_f32 v3, v6, v4
	v_mul_f32_e32 v5, 0x45000000, v7
	v_mul_f32_e32 v4, 0x45000000, v57
	v_med3_f32 v5, v5, s63, v144
	v_med3_f32 v4, v4, s63, v144
	v_add_u32_e32 v6, s0, v81
	v_cvt_pk_fp8_f32 v3, v5, v4 op_sel:[0,0,1]
	v_ashrrev_i32_e32 v4, 3, v6
	v_and_b32_e32 v4, 0xffffffe0, v4
	v_or_b32_e32 v4, s1, v4
	v_ashrrev_i32_e32 v5, 31, v4
	v_lshlrev_b64 v[4:5], 15, v[4:5]
	v_lshlrev_b32_e32 v6, 7, v6
	v_and_b32_e32 v64, 0x7f80, v6
	v_lshl_add_u64 v[4:5], s[22:23], 0, v[4:5]
	v_lshl_add_u64 v[4:5], v[4:5], 0, v[64:65]
	v_add_u32_e32 v64, v87, v84
	v_add_u32_e32 v92, 0x1000, v64
	ds_read2_b32 v[56:57], v92 offset1:32
	ds_read2_b32 v[6:7], v64 offset1:32
	v_lshl_add_u64 v[4:5], v[4:5], 0, v[44:45]
	v_add_u32_e32 v93, 0x2000, v64
	global_store_dwordx4 v[4:5], v[0:3], off
	ds_read2_b32 v[58:59], v93 offset1:32
	s_waitcnt lgkmcnt(0)
	v_mul_f32_e32 v4, 0x45000000, v58
	v_mul_f32_e32 v1, 0x45000000, v56
	v_add_u32_e32 v56, 0x3000, v64
	ds_read2_b32 v[2:3], v56 offset1:32
	v_mul_f32_e32 v0, 0x45000000, v6
	v_med3_f32 v5, v0, s63, v144
	v_med3_f32 v1, v1, s63, v144
	v_mov_b32_e32 v0, v65
	v_cvt_pk_fp8_f32 v0, v5, v1
	s_waitcnt lgkmcnt(0)
	v_mul_f32_e32 v1, 0x45000000, v2
	v_med3_f32 v2, v4, s63, v144
	v_med3_f32 v1, v1, s63, v144
	v_cvt_pk_fp8_f32 v0, v2, v1 op_sel:[0,0,1]
	v_mul_f32_e32 v1, 0x45000000, v7
	v_mul_f32_e32 v2, 0x45000000, v57
	v_mul_f32_e32 v57, 0x45000000, v3
	v_med3_f32 v3, v1, s63, v144
	v_med3_f32 v2, v2, s63, v144
	v_mov_b32_e32 v1, v65
	v_mul_f32_e32 v4, 0x45000000, v59
	v_cvt_pk_fp8_f32 v1, v3, v2
	v_med3_f32 v58, v4, s63, v144
	ds_read2_b32 v[2:3], v64 offset0:64 offset1:96
	ds_read2_b32 v[4:5], v92 offset0:64 offset1:96
	ds_read2_b32 v[6:7], v93 offset0:64 offset1:96
	v_med3_f32 v57, v57, s63, v144
	v_cvt_pk_fp8_f32 v1, v58, v57 op_sel:[0,0,1]
	ds_read2_b32 v[56:57], v56 offset0:64 offset1:96
	s_waitcnt lgkmcnt(3)
	v_mul_f32_e32 v2, 0x45000000, v2
	s_waitcnt lgkmcnt(2)
	v_mul_f32_e32 v4, 0x45000000, v4
	v_med3_f32 v58, v2, s63, v144
	v_med3_f32 v4, v4, s63, v144
	v_mov_b32_e32 v2, v65
	v_cvt_pk_fp8_f32 v2, v58, v4
	s_waitcnt lgkmcnt(1)
	v_mul_f32_e32 v6, 0x45000000, v6
	s_waitcnt lgkmcnt(0)
	v_mul_f32_e32 v4, 0x45000000, v56
	v_med3_f32 v6, v6, s63, v144
	v_med3_f32 v4, v4, s63, v144
	v_cvt_pk_fp8_f32 v2, v6, v4 op_sel:[0,0,1]
	v_mul_f32_e32 v3, 0x45000000, v3
	v_mul_f32_e32 v4, 0x45000000, v5
	v_med3_f32 v6, v3, s63, v144
	v_med3_f32 v4, v4, s63, v144
	v_mov_b32_e32 v3, v65
	v_cvt_pk_fp8_f32 v3, v6, v4
	v_mul_f32_e32 v5, 0x45000000, v7
	v_mul_f32_e32 v4, 0x45000000, v57
	v_med3_f32 v5, v5, s63, v144
	v_med3_f32 v4, v4, s63, v144
	v_add_u32_e32 v6, s0, v82
	v_cvt_pk_fp8_f32 v3, v5, v4 op_sel:[0,0,1]
	v_ashrrev_i32_e32 v4, 3, v6
	v_and_b32_e32 v4, 0xffffffe0, v4
	v_or_b32_e32 v4, s1, v4
	v_ashrrev_i32_e32 v5, 31, v4
	v_lshlrev_b64 v[4:5], 15, v[4:5]
	v_lshlrev_b32_e32 v6, 7, v6
	v_and_b32_e32 v64, 0x7f80, v6
	v_lshl_add_u64 v[4:5], s[22:23], 0, v[4:5]
	v_lshl_add_u64 v[4:5], v[4:5], 0, v[64:65]
	v_add_u32_e32 v64, v88, v84
	v_add_u32_e32 v92, 0x1000, v64
	ds_read2_b32 v[56:57], v92 offset1:32
	ds_read2_b32 v[6:7], v64 offset1:32
	v_lshl_add_u64 v[4:5], v[4:5], 0, v[44:45]
	v_add_u32_e32 v93, 0x2000, v64
	global_store_dwordx4 v[4:5], v[0:3], off
	ds_read2_b32 v[58:59], v93 offset1:32
	s_waitcnt lgkmcnt(0)
	v_mul_f32_e32 v4, 0x45000000, v58
	v_mul_f32_e32 v1, 0x45000000, v56
	v_add_u32_e32 v56, 0x3000, v64
	ds_read2_b32 v[2:3], v56 offset1:32
	v_mul_f32_e32 v0, 0x45000000, v6
	v_med3_f32 v5, v0, s63, v144
	v_med3_f32 v1, v1, s63, v144
	v_mov_b32_e32 v0, v65
	v_cvt_pk_fp8_f32 v0, v5, v1
	s_waitcnt lgkmcnt(0)
	v_mul_f32_e32 v1, 0x45000000, v2
	v_med3_f32 v2, v4, s63, v144
	v_med3_f32 v1, v1, s63, v144
	v_cvt_pk_fp8_f32 v0, v2, v1 op_sel:[0,0,1]
	v_mul_f32_e32 v1, 0x45000000, v7
	v_mul_f32_e32 v2, 0x45000000, v57
	v_mul_f32_e32 v57, 0x45000000, v3
	v_med3_f32 v3, v1, s63, v144
	v_med3_f32 v2, v2, s63, v144
	v_mov_b32_e32 v1, v65
	v_mul_f32_e32 v4, 0x45000000, v59
	v_cvt_pk_fp8_f32 v1, v3, v2
	v_med3_f32 v58, v4, s63, v144
	ds_read2_b32 v[2:3], v64 offset0:64 offset1:96
	ds_read2_b32 v[4:5], v92 offset0:64 offset1:96
	ds_read2_b32 v[6:7], v93 offset0:64 offset1:96
	v_med3_f32 v57, v57, s63, v144
	v_cvt_pk_fp8_f32 v1, v58, v57 op_sel:[0,0,1]
	ds_read2_b32 v[56:57], v56 offset0:64 offset1:96
	s_waitcnt lgkmcnt(3)
	v_mul_f32_e32 v2, 0x45000000, v2
	s_waitcnt lgkmcnt(2)
	v_mul_f32_e32 v4, 0x45000000, v4
	v_med3_f32 v58, v2, s63, v144
	v_med3_f32 v4, v4, s63, v144
	v_mov_b32_e32 v2, v65
	v_cvt_pk_fp8_f32 v2, v58, v4
	s_waitcnt lgkmcnt(1)
	v_mul_f32_e32 v6, 0x45000000, v6
	s_waitcnt lgkmcnt(0)
	v_mul_f32_e32 v4, 0x45000000, v56
	v_med3_f32 v6, v6, s63, v144
	v_med3_f32 v4, v4, s63, v144
	v_cvt_pk_fp8_f32 v2, v6, v4 op_sel:[0,0,1]
	v_mul_f32_e32 v3, 0x45000000, v3
	v_mul_f32_e32 v4, 0x45000000, v5
	v_med3_f32 v6, v3, s63, v144
	v_med3_f32 v4, v4, s63, v144
	v_mov_b32_e32 v3, v65
	v_cvt_pk_fp8_f32 v3, v6, v4
	v_mul_f32_e32 v5, 0x45000000, v7
	v_mul_f32_e32 v4, 0x45000000, v57
	v_med3_f32 v5, v5, s63, v144
	v_med3_f32 v4, v4, s63, v144
	v_add_u32_e32 v6, s0, v83
	v_cvt_pk_fp8_f32 v3, v5, v4 op_sel:[0,0,1]
	v_ashrrev_i32_e32 v4, 3, v6
	v_and_b32_e32 v4, 0xffffffe0, v4
	v_or_b32_e32 v4, s1, v4
	v_ashrrev_i32_e32 v5, 31, v4
	v_lshlrev_b64 v[4:5], 15, v[4:5]
	v_lshlrev_b32_e32 v6, 7, v6
	v_and_b32_e32 v64, 0x7f80, v6
	v_lshl_add_u64 v[4:5], s[22:23], 0, v[4:5]
	v_lshl_add_u64 v[4:5], v[4:5], 0, v[64:65]
	v_lshl_add_u64 v[4:5], v[4:5], 0, v[44:45]
	global_store_dwordx4 v[4:5], v[0:3], off
	s_waitcnt lgkmcnt(0)

.LBB0_51:
	s_lshl_b32 s69, s66, 1
	s_lshl_b32 s68, s33, 1
	v_add_u32_e32 v6, s69, v10
	v_add_u32_e32 v7, s68, v9
	v_add_u32_e32 v2, s1, v6
	v_add_u32_e32 v4, s28, v7
	v_mad_i64_i32 v[2:3], s[70:71], v2, s64, v[0:1]
	v_mad_i64_i32 v[4:5], s[70:71], v4, s64, v[0:1]
	global_load_dword v163, v[2:3], off
	s_nop 0
	global_load_dword v164, v[4:5], off
	v_lshrrev_b32_e32 v5, 2, v6
	v_lshrrev_b32_e32 v4, 2, v7
	v_and_b32_e32 v5, 28, v5
	v_and_b32_e32 v4, 28, v4
	v_xor_b32_e32 v5, v5, v12
	v_xor_b32_e32 v4, v4, v11
	v_lshlrev_b32_e32 v6, 7, v6
	v_lshlrev_b32_e32 v5, 2, v5
	v_lshlrev_b32_e32 v7, 7, v7
	v_add3_u32 v195, s37, v6, v5
	v_lshlrev_b32_e32 v4, 2, v4
	v_add_u32_e32 v6, s69, v14
	v_add3_u32 v196, s37, v7, v4
	v_add_u32_e32 v7, s68, v13
	s_add_i32 s66, s66, 32
	s_add_i32 s33, s33, 32
	s_sub_i32 s67, s67, 32
	s_cmp_lg_u32 s67, 0
	v_add_u32_e32 v2, s1, v6
	v_add_u32_e32 v4, s28, v7
	v_mad_i64_i32 v[2:3], s[70:71], v2, s64, v[0:1]
	v_mad_i64_i32 v[4:5], s[70:71], v4, s64, v[0:1]
	global_load_dword v165, v[2:3], off
	s_nop 0
	global_load_dword v166, v[4:5], off
	v_lshrrev_b32_e32 v5, 2, v6
	v_lshrrev_b32_e32 v4, 2, v7
	v_and_b32_e32 v5, 28, v5
	v_and_b32_e32 v4, 28, v4
	v_xor_b32_e32 v5, v5, v12
	v_xor_b32_e32 v4, v4, v11
	v_lshlrev_b32_e32 v6, 7, v6
	v_lshlrev_b32_e32 v5, 2, v5
	v_lshlrev_b32_e32 v7, 7, v7
	v_add3_u32 v197, s37, v6, v5
	v_lshlrev_b32_e32 v4, 2, v4
	v_add_u32_e32 v6, s69, v16
	v_add3_u32 v198, s37, v7, v4
	v_add_u32_e32 v7, s68, v15
	v_add_u32_e32 v2, s1, v6
	v_add_u32_e32 v4, s28, v7
	v_mad_i64_i32 v[2:3], s[70:71], v2, s64, v[0:1]
	v_mad_i64_i32 v[4:5], s[70:71], v4, s64, v[0:1]
	global_load_dword v167, v[2:3], off
	s_nop 0
	global_load_dword v168, v[4:5], off
	v_lshrrev_b32_e32 v5, 2, v6
	v_lshrrev_b32_e32 v4, 2, v7
	v_and_b32_e32 v5, 28, v5
	v_and_b32_e32 v4, 28, v4
	v_xor_b32_e32 v5, v5, v12
	v_xor_b32_e32 v4, v4, v11
	v_lshlrev_b32_e32 v6, 7, v6
	v_lshlrev_b32_e32 v5, 2, v5
	v_lshlrev_b32_e32 v7, 7, v7
	v_add3_u32 v199, s37, v6, v5
	v_lshlrev_b32_e32 v4, 2, v4
	v_add_u32_e32 v6, s69, v18
	v_add3_u32 v200, s37, v7, v4
	v_add_u32_e32 v7, s68, v17
	v_add_u32_e32 v2, s1, v6
	v_add_u32_e32 v4, s28, v7
	v_mad_i64_i32 v[2:3], s[70:71], v2, s64, v[0:1]
	v_mad_i64_i32 v[4:5], s[70:71], v4, s64, v[0:1]
	global_load_dword v169, v[2:3], off
	s_nop 0
	global_load_dword v170, v[4:5], off
	v_lshrrev_b32_e32 v5, 2, v6
	v_lshrrev_b32_e32 v4, 2, v7
	v_and_b32_e32 v5, 28, v5
	v_and_b32_e32 v4, 28, v4
	v_xor_b32_e32 v5, v5, v12
	v_xor_b32_e32 v4, v4, v11
	v_lshlrev_b32_e32 v6, 7, v6
	v_lshlrev_b32_e32 v5, 2, v5
	v_lshlrev_b32_e32 v7, 7, v7
	v_add3_u32 v201, s37, v6, v5
	v_lshlrev_b32_e32 v4, 2, v4
	v_add_u32_e32 v6, s69, v20
	v_add3_u32 v202, s37, v7, v4
	v_add_u32_e32 v7, s68, v19
	v_add_u32_e32 v2, s1, v6
	v_add_u32_e32 v4, s28, v7
	v_mad_i64_i32 v[2:3], s[70:71], v2, s64, v[0:1]
	v_mad_i64_i32 v[4:5], s[70:71], v4, s64, v[0:1]
	global_load_dword v171, v[2:3], off
	s_nop 0
	global_load_dword v172, v[4:5], off
	v_lshrrev_b32_e32 v5, 2, v6
	v_lshrrev_b32_e32 v4, 2, v7
	v_and_b32_e32 v5, 28, v5
	v_and_b32_e32 v4, 28, v4
	v_xor_b32_e32 v5, v5, v12
	v_xor_b32_e32 v4, v4, v11
	v_lshlrev_b32_e32 v6, 7, v6
	v_lshlrev_b32_e32 v5, 2, v5
	v_lshlrev_b32_e32 v7, 7, v7
	v_add3_u32 v203, s37, v6, v5
	v_lshlrev_b32_e32 v4, 2, v4
	v_add_u32_e32 v6, s69, v22
	v_add3_u32 v204, s37, v7, v4
	v_add_u32_e32 v7, s68, v21
	v_add_u32_e32 v2, s1, v6
	v_add_u32_e32 v4, s28, v7
	v_mad_i64_i32 v[2:3], s[70:71], v2, s64, v[0:1]
	v_mad_i64_i32 v[4:5], s[70:71], v4, s64, v[0:1]
	global_load_dword v173, v[2:3], off
	s_nop 0
	global_load_dword v174, v[4:5], off
	v_lshrrev_b32_e32 v5, 2, v6
	v_lshrrev_b32_e32 v4, 2, v7
	v_and_b32_e32 v5, 28, v5
	v_and_b32_e32 v4, 28, v4
	v_xor_b32_e32 v5, v5, v12
	v_xor_b32_e32 v4, v4, v11
	v_lshlrev_b32_e32 v6, 7, v6
	v_lshlrev_b32_e32 v5, 2, v5
	v_lshlrev_b32_e32 v7, 7, v7
	v_add3_u32 v205, s37, v6, v5
	v_lshlrev_b32_e32 v4, 2, v4
	v_add_u32_e32 v6, s69, v24
	v_add3_u32 v206, s37, v7, v4
	v_add_u32_e32 v7, s68, v23
	v_add_u32_e32 v2, s1, v6
	v_add_u32_e32 v4, s28, v7
	v_mad_i64_i32 v[2:3], s[70:71], v2, s64, v[0:1]
	v_mad_i64_i32 v[4:5], s[70:71], v4, s64, v[0:1]
	global_load_dword v175, v[2:3], off
	s_nop 0
	global_load_dword v176, v[4:5], off
	v_lshrrev_b32_e32 v5, 2, v6
	v_lshrrev_b32_e32 v4, 2, v7
	v_and_b32_e32 v5, 28, v5
	v_and_b32_e32 v4, 28, v4
	v_xor_b32_e32 v5, v5, v12
	v_xor_b32_e32 v4, v4, v11
	v_lshlrev_b32_e32 v6, 7, v6
	v_lshlrev_b32_e32 v5, 2, v5
	v_lshlrev_b32_e32 v7, 7, v7
	v_add3_u32 v207, s37, v6, v5
	v_lshlrev_b32_e32 v4, 2, v4
	v_add_u32_e32 v6, s69, v26
	v_add3_u32 v208, s37, v7, v4
	v_add_u32_e32 v7, s68, v25
	v_add_u32_e32 v2, s1, v6
	v_add_u32_e32 v4, s28, v7
	v_mad_i64_i32 v[2:3], s[70:71], v2, s64, v[0:1]
	v_mad_i64_i32 v[4:5], s[70:71], v4, s64, v[0:1]
	global_load_dword v177, v[2:3], off
	s_nop 0
	global_load_dword v178, v[4:5], off
	v_lshrrev_b32_e32 v5, 2, v6
	v_lshrrev_b32_e32 v4, 2, v7
	v_and_b32_e32 v5, 28, v5
	v_and_b32_e32 v4, 28, v4
	v_xor_b32_e32 v5, v5, v12
	v_xor_b32_e32 v4, v4, v11
	v_lshlrev_b32_e32 v6, 7, v6
	v_lshlrev_b32_e32 v5, 2, v5
	v_lshlrev_b32_e32 v7, 7, v7
	v_add3_u32 v209, s37, v6, v5
	v_lshlrev_b32_e32 v4, 2, v4
	v_add_u32_e32 v6, s69, v28
	v_add3_u32 v210, s37, v7, v4
	v_add_u32_e32 v7, s68, v27
	v_add_u32_e32 v2, s1, v6
	v_add_u32_e32 v4, s28, v7
	v_mad_i64_i32 v[2:3], s[70:71], v2, s64, v[0:1]
	v_mad_i64_i32 v[4:5], s[70:71], v4, s64, v[0:1]
	global_load_dword v179, v[2:3], off
	s_nop 0
	global_load_dword v180, v[4:5], off
	v_lshrrev_b32_e32 v5, 2, v6
	v_lshrrev_b32_e32 v4, 2, v7
	v_and_b32_e32 v5, 28, v5
	v_and_b32_e32 v4, 28, v4
	v_xor_b32_e32 v5, v5, v12
	v_xor_b32_e32 v4, v4, v11
	v_lshlrev_b32_e32 v6, 7, v6
	v_lshlrev_b32_e32 v5, 2, v5
	v_lshlrev_b32_e32 v7, 7, v7
	v_add3_u32 v211, s37, v6, v5
	v_lshlrev_b32_e32 v4, 2, v4
	v_add_u32_e32 v6, s69, v30
	v_add3_u32 v212, s37, v7, v4
	v_add_u32_e32 v7, s68, v29
	v_add_u32_e32 v2, s1, v6
	v_add_u32_e32 v4, s28, v7
	v_mad_i64_i32 v[2:3], s[70:71], v2, s64, v[0:1]
	v_mad_i64_i32 v[4:5], s[70:71], v4, s64, v[0:1]
	global_load_dword v181, v[2:3], off
	s_nop 0
	global_load_dword v182, v[4:5], off
	v_lshrrev_b32_e32 v5, 2, v6
	v_lshrrev_b32_e32 v4, 2, v7
	v_and_b32_e32 v5, 28, v5
	v_and_b32_e32 v4, 28, v4
	v_xor_b32_e32 v5, v5, v12
	v_xor_b32_e32 v4, v4, v11
	v_lshlrev_b32_e32 v6, 7, v6
	v_lshlrev_b32_e32 v5, 2, v5
	v_lshlrev_b32_e32 v7, 7, v7
	v_add3_u32 v213, s37, v6, v5
	v_lshlrev_b32_e32 v4, 2, v4
	v_add_u32_e32 v6, s69, v32
	v_add3_u32 v214, s37, v7, v4
	v_add_u32_e32 v7, s68, v31
	v_add_u32_e32 v2, s1, v6
	v_add_u32_e32 v4, s28, v7
	v_mad_i64_i32 v[2:3], s[70:71], v2, s64, v[0:1]
	v_mad_i64_i32 v[4:5], s[70:71], v4, s64, v[0:1]
	global_load_dword v183, v[2:3], off
	s_nop 0
	global_load_dword v184, v[4:5], off
	v_lshrrev_b32_e32 v5, 2, v6
	v_lshrrev_b32_e32 v4, 2, v7
	v_and_b32_e32 v5, 28, v5
	v_and_b32_e32 v4, 28, v4
	v_xor_b32_e32 v5, v5, v12
	v_xor_b32_e32 v4, v4, v11
	v_lshlrev_b32_e32 v6, 7, v6
	v_lshlrev_b32_e32 v5, 2, v5
	v_lshlrev_b32_e32 v7, 7, v7
	v_add3_u32 v215, s37, v6, v5
	v_lshlrev_b32_e32 v4, 2, v4
	v_add_u32_e32 v6, s69, v34
	v_add3_u32 v216, s37, v7, v4
	v_add_u32_e32 v7, s68, v33
	v_add_u32_e32 v2, s1, v6
	v_add_u32_e32 v4, s28, v7
	v_mad_i64_i32 v[2:3], s[70:71], v2, s64, v[0:1]
	v_mad_i64_i32 v[4:5], s[70:71], v4, s64, v[0:1]
	global_load_dword v185, v[2:3], off
	s_nop 0
	global_load_dword v186, v[4:5], off
	v_lshrrev_b32_e32 v5, 2, v6
	v_lshrrev_b32_e32 v4, 2, v7
	v_and_b32_e32 v5, 28, v5
	v_and_b32_e32 v4, 28, v4
	v_xor_b32_e32 v5, v5, v12
	v_xor_b32_e32 v4, v4, v11
	v_lshlrev_b32_e32 v6, 7, v6
	v_lshlrev_b32_e32 v5, 2, v5
	v_lshlrev_b32_e32 v7, 7, v7
	v_add3_u32 v217, s37, v6, v5
	v_lshlrev_b32_e32 v4, 2, v4
	v_add_u32_e32 v6, s69, v36
	v_add3_u32 v218, s37, v7, v4
	v_add_u32_e32 v7, s68, v35
	v_add_u32_e32 v2, s1, v6
	v_add_u32_e32 v4, s28, v7
	v_mad_i64_i32 v[2:3], s[70:71], v2, s64, v[0:1]
	v_mad_i64_i32 v[4:5], s[70:71], v4, s64, v[0:1]
	global_load_dword v187, v[2:3], off
	s_nop 0
	global_load_dword v188, v[4:5], off
	v_lshrrev_b32_e32 v5, 2, v6
	v_lshrrev_b32_e32 v4, 2, v7
	v_and_b32_e32 v5, 28, v5
	v_and_b32_e32 v4, 28, v4
	v_xor_b32_e32 v5, v5, v12
	v_xor_b32_e32 v4, v4, v11
	v_lshlrev_b32_e32 v6, 7, v6
	v_lshlrev_b32_e32 v5, 2, v5
	v_lshlrev_b32_e32 v7, 7, v7
	v_add3_u32 v219, s37, v6, v5
	v_lshlrev_b32_e32 v4, 2, v4
	v_add_u32_e32 v6, s69, v38
	v_add3_u32 v220, s37, v7, v4
	v_add_u32_e32 v7, s68, v37
	v_add_u32_e32 v2, s1, v6
	v_add_u32_e32 v4, s28, v7
	v_mad_i64_i32 v[2:3], s[70:71], v2, s64, v[0:1]
	v_mad_i64_i32 v[4:5], s[70:71], v4, s64, v[0:1]
	global_load_dword v189, v[2:3], off
	s_nop 0
	global_load_dword v190, v[4:5], off
	v_lshrrev_b32_e32 v5, 2, v6
	v_lshrrev_b32_e32 v4, 2, v7
	v_and_b32_e32 v5, 28, v5
	v_and_b32_e32 v4, 28, v4
	v_xor_b32_e32 v5, v5, v12
	v_xor_b32_e32 v4, v4, v11
	v_lshlrev_b32_e32 v6, 7, v6
	v_lshlrev_b32_e32 v5, 2, v5
	v_lshlrev_b32_e32 v7, 7, v7
	v_add3_u32 v221, s37, v6, v5
	v_lshlrev_b32_e32 v4, 2, v4
	v_add_u32_e32 v6, s69, v40
	v_add3_u32 v222, s37, v7, v4
	v_add_u32_e32 v7, s68, v39
	v_add_u32_e32 v2, s1, v6
	v_add_u32_e32 v4, s28, v7
	v_mad_i64_i32 v[2:3], s[70:71], v2, s64, v[0:1]
	v_mad_i64_i32 v[4:5], s[70:71], v4, s64, v[0:1]
	global_load_dword v191, v[2:3], off
	s_nop 0
	global_load_dword v192, v[4:5], off
	v_lshrrev_b32_e32 v5, 2, v6
	v_lshrrev_b32_e32 v4, 2, v7
	v_and_b32_e32 v5, 28, v5
	v_and_b32_e32 v4, 28, v4
	v_xor_b32_e32 v5, v5, v12
	v_xor_b32_e32 v4, v4, v11
	v_lshlrev_b32_e32 v6, 7, v6
	v_lshlrev_b32_e32 v5, 2, v5
	v_lshlrev_b32_e32 v7, 7, v7
	v_add3_u32 v223, s37, v6, v5
	v_lshlrev_b32_e32 v4, 2, v4
	v_add_u32_e32 v6, s69, v42
	v_add3_u32 v224, s37, v7, v4
	v_add_u32_e32 v7, s68, v41
	v_add_u32_e32 v2, s1, v6
	v_add_u32_e32 v4, s28, v7
	v_mad_i64_i32 v[2:3], s[68:69], v2, s64, v[0:1]
	v_mad_i64_i32 v[4:5], s[68:69], v4, s64, v[0:1]
	global_load_dword v193, v[2:3], off
	s_nop 0
	global_load_dword v194, v[4:5], off
	v_lshrrev_b32_e32 v5, 2, v6
	v_lshrrev_b32_e32 v4, 2, v7
	v_and_b32_e32 v5, 28, v5
	v_and_b32_e32 v4, 28, v4
	v_xor_b32_e32 v5, v5, v12
	v_xor_b32_e32 v4, v4, v11
	v_lshlrev_b32_e32 v6, 7, v6
	v_lshlrev_b32_e32 v5, 2, v5
	v_lshlrev_b32_e32 v7, 7, v7
	v_add3_u32 v225, s37, v6, v5
	v_lshlrev_b32_e32 v4, 2, v4
	v_add3_u32 v226, s37, v7, v4
	s_waitcnt vmcnt(0)
	ds_write_b32 v195, v163
	ds_write_b32 v196, v164
	ds_write_b32 v197, v165
	ds_write_b32 v198, v166
	ds_write_b32 v199, v167
	ds_write_b32 v200, v168
	ds_write_b32 v201, v169
	ds_write_b32 v202, v170
	ds_write_b32 v203, v171
	ds_write_b32 v204, v172
	ds_write_b32 v205, v173
	ds_write_b32 v206, v174
	ds_write_b32 v207, v175
	ds_write_b32 v208, v176
	ds_write_b32 v209, v177
	ds_write_b32 v210, v178
	ds_write_b32 v211, v179
	ds_write_b32 v212, v180
	ds_write_b32 v213, v181
	ds_write_b32 v214, v182
	ds_write_b32 v215, v183
	ds_write_b32 v216, v184
	ds_write_b32 v217, v185
	ds_write_b32 v218, v186
	ds_write_b32 v219, v187
	ds_write_b32 v220, v188
	ds_write_b32 v221, v189
	ds_write_b32 v222, v190
	ds_write_b32 v223, v191
	ds_write_b32 v224, v192
	ds_write_b32 v225, v193
	ds_write_b32 v226, v194
	s_cbranch_scc1 .LBB0_51
	s_waitcnt lgkmcnt(0)
	v_add_u32_e32 v6, v85, v89
	ds_read2_b32 v[0:1], v6 offset1:32
	ds_read2_b32 v[2:3], v6 offset0:64 offset1:96
	ds_read2_b32 v[4:5], v6 offset0:192 offset1:224
	v_add_u32_e32 v58, v86, v89
	s_waitcnt lgkmcnt(2)
	v_mul_f32_e32 v0, 0x44f00000, v0
	s_waitcnt lgkmcnt(1)
	v_mul_f32_e32 v2, 0x44f00000, v2
	v_mul_f32_e32 v3, 0x44f00000, v3
	v_med3_f32 v2, v2, s44, v143
	v_add_f32_e32 v7, 0x4b400000, v2
	v_med3_f32 v2, v3, s44, v143
	v_add_f32_e32 v56, 0x4b400000, v2
	ds_read2_b32 v[2:3], v6 offset0:128 offset1:160
	v_mul_f32_e32 v1, 0x44f00000, v1
	v_med3_f32 v0, v0, s44, v143
	v_med3_f32 v1, v1, s44, v143
	v_add_f32_e32 v0, 0x4b400000, v0
	v_add_f32_e32 v1, 0x4b400000, v1
	v_perm_b32 v0, v1, v0, s45
	v_perm_b32 v1, v56, v7, s45
	v_lshl_or_b32 v0, v1, 16, v0
	s_waitcnt lgkmcnt(0)
	v_mul_f32_e32 v1, 0x44f00000, v2
	v_mul_f32_e32 v2, 0x44f00000, v3
	v_mul_f32_e32 v3, 0x44f00000, v4
	v_med3_f32 v1, v1, s44, v143
	v_med3_f32 v2, v2, s44, v143
	v_mul_f32_e32 v4, 0x44f00000, v5
	v_add_f32_e32 v1, 0x4b400000, v1
	v_add_f32_e32 v5, 0x4b400000, v2
	v_med3_f32 v2, v3, s44, v143
	v_add_u32_e32 v6, 0x400, v6
	v_add_f32_e32 v7, 0x4b400000, v2
	v_med3_f32 v2, v4, s44, v143
	v_perm_b32 v1, v5, v1, s45
	ds_read2_b32 v[4:5], v6 offset0:64 offset1:96
	v_add_f32_e32 v56, 0x4b400000, v2
	ds_read2_b32 v[2:3], v6 offset1:32
	v_perm_b32 v7, v56, v7, s45
	v_lshl_or_b32 v1, v7, 16, v1
	s_waitcnt lgkmcnt(1)
	v_mul_f32_e32 v4, 0x44f00000, v4
	v_mul_f32_e32 v5, 0x44f00000, v5
	v_med3_f32 v4, v4, s44, v143
	v_add_f32_e32 v56, 0x4b400000, v4
	v_med3_f32 v4, v5, s44, v143
	v_add_f32_e32 v57, 0x4b400000, v4
	ds_read2_b32 v[4:5], v6 offset0:128 offset1:160
	ds_read2_b32 v[6:7], v6 offset0:192 offset1:224
	s_waitcnt lgkmcnt(2)
	v_mul_f32_e32 v2, 0x44f00000, v2
	v_mul_f32_e32 v3, 0x44f00000, v3
	v_med3_f32 v2, v2, s44, v143
	v_med3_f32 v3, v3, s44, v143
	v_add_f32_e32 v2, 0x4b400000, v2
	v_add_f32_e32 v3, 0x4b400000, v3
	v_perm_b32 v2, v3, v2, s45
	v_perm_b32 v3, v57, v56, s45
	v_lshl_or_b32 v2, v3, 16, v2
	s_waitcnt lgkmcnt(1)
	v_mul_f32_e32 v3, 0x44f00000, v4
	v_mul_f32_e32 v4, 0x44f00000, v5
	s_waitcnt lgkmcnt(0)
	v_mul_f32_e32 v5, 0x44f00000, v6
	v_mul_f32_e32 v6, 0x44f00000, v7
	v_med3_f32 v3, v3, s44, v143
	v_med3_f32 v4, v4, s44, v143
	v_med3_f32 v5, v5, s44, v143
	v_med3_f32 v6, v6, s44, v143
	v_add_f32_e32 v3, 0x4b400000, v3
	v_add_f32_e32 v4, 0x4b400000, v4
	v_add_f32_e32 v5, 0x4b400000, v5
	v_add_f32_e32 v6, 0x4b400000, v6
	v_perm_b32 v3, v4, v3, s45
	v_perm_b32 v4, v6, v5, s45
	v_add_u32_e32 v6, s0, v66
	v_lshl_or_b32 v3, v4, 16, v3
	v_ashrrev_i32_e32 v4, 3, v6
	v_and_b32_e32 v4, 0xffffffe0, v4
	v_add_u32_e32 v4, s9, v4
	v_ashrrev_i32_e32 v5, 31, v4
	ds_read2_b32 v[56:57], v58 offset0:64 offset1:96
	v_lshlrev_b64 v[4:5], 15, v[4:5]
	v_lshlrev_b32_e32 v6, 7, v6
	v_and_b32_e32 v64, 0x7f80, v6
	v_lshl_add_u64 v[4:5], s[24:25], 0, v[4:5]
	ds_read2_b32 v[6:7], v58 offset1:32
	v_lshl_add_u64 v[4:5], v[4:5], 0, v[64:65]
	v_lshl_add_u64 v[4:5], v[4:5], 0, v[44:45]
	global_store_dwordx4 v[4:5], v[0:3], off
	ds_read2_b32 v[4:5], v58 offset0:192 offset1:224
	s_waitcnt lgkmcnt(2)
	v_mul_f32_e32 v2, 0x44f00000, v56
	v_mul_f32_e32 v3, 0x44f00000, v57
	v_med3_f32 v2, v2, s44, v143
	s_waitcnt lgkmcnt(1)
	v_mul_f32_e32 v0, 0x44f00000, v6
	v_add_f32_e32 v6, 0x4b400000, v2
	v_med3_f32 v2, v3, s44, v143
	v_mul_f32_e32 v1, 0x44f00000, v7
	v_add_f32_e32 v7, 0x4b400000, v2
	ds_read2_b32 v[2:3], v58 offset0:128 offset1:160
	v_med3_f32 v0, v0, s44, v143
	v_med3_f32 v1, v1, s44, v143
	v_add_f32_e32 v0, 0x4b400000, v0
	v_add_f32_e32 v1, 0x4b400000, v1
	v_perm_b32 v0, v1, v0, s45
	v_perm_b32 v1, v7, v6, s45
	v_lshl_or_b32 v0, v1, 16, v0
	s_waitcnt lgkmcnt(0)
	v_mul_f32_e32 v1, 0x44f00000, v2
	v_mul_f32_e32 v2, 0x44f00000, v3
	v_mul_f32_e32 v3, 0x44f00000, v4
	v_med3_f32 v1, v1, s44, v143
	v_med3_f32 v2, v2, s44, v143
	v_mul_f32_e32 v4, 0x44f00000, v5
	v_add_f32_e32 v1, 0x4b400000, v1
	v_add_f32_e32 v5, 0x4b400000, v2
	v_med3_f32 v2, v3, s44, v143
	v_add_u32_e32 v56, 0x400, v58
	v_add_f32_e32 v6, 0x4b400000, v2
	v_med3_f32 v2, v4, s44, v143
	v_perm_b32 v1, v5, v1, s45
	ds_read2_b32 v[4:5], v56 offset0:64 offset1:96
	v_add_f32_e32 v7, 0x4b400000, v2
	ds_read2_b32 v[2:3], v56 offset1:32
	v_perm_b32 v6, v7, v6, s45
	v_lshl_or_b32 v1, v6, 16, v1
	s_waitcnt lgkmcnt(1)
	v_mul_f32_e32 v4, 0x44f00000, v4
	v_mul_f32_e32 v5, 0x44f00000, v5
	v_med3_f32 v4, v4, s44, v143
	v_add_f32_e32 v57, 0x4b400000, v4
	v_med3_f32 v4, v5, s44, v143
	v_add_f32_e32 v58, 0x4b400000, v4
	ds_read2_b32 v[4:5], v56 offset0:128 offset1:160
	ds_read2_b32 v[6:7], v56 offset0:192 offset1:224
	s_waitcnt lgkmcnt(2)
	v_mul_f32_e32 v2, 0x44f00000, v2
	v_mul_f32_e32 v3, 0x44f00000, v3
	v_med3_f32 v2, v2, s44, v143
	v_med3_f32 v3, v3, s44, v143
	v_add_f32_e32 v2, 0x4b400000, v2
	v_add_f32_e32 v3, 0x4b400000, v3
	v_perm_b32 v2, v3, v2, s45
	v_perm_b32 v3, v58, v57, s45
	v_lshl_or_b32 v2, v3, 16, v2
	s_waitcnt lgkmcnt(1)
	v_mul_f32_e32 v3, 0x44f00000, v4
	v_mul_f32_e32 v4, 0x44f00000, v5
	s_waitcnt lgkmcnt(0)
	v_mul_f32_e32 v5, 0x44f00000, v6
	v_mul_f32_e32 v6, 0x44f00000, v7
	v_med3_f32 v3, v3, s44, v143
	v_med3_f32 v4, v4, s44, v143
	v_med3_f32 v5, v5, s44, v143
	v_med3_f32 v6, v6, s44, v143
	v_add_f32_e32 v3, 0x4b400000, v3
	v_add_f32_e32 v4, 0x4b400000, v4
	v_add_f32_e32 v5, 0x4b400000, v5
	v_add_f32_e32 v6, 0x4b400000, v6
	v_perm_b32 v3, v4, v3, s45
	v_perm_b32 v4, v6, v5, s45
	v_add_u32_e32 v6, s0, v81
	v_lshl_or_b32 v3, v4, 16, v3
	v_ashrrev_i32_e32 v4, 3, v6
	v_and_b32_e32 v4, 0xffffffe0, v4
	v_add_u32_e32 v4, s9, v4
	v_add_u32_e32 v58, v87, v89
	v_ashrrev_i32_e32 v5, 31, v4
	ds_read2_b32 v[56:57], v58 offset0:64 offset1:96
	v_lshlrev_b64 v[4:5], 15, v[4:5]
	v_lshlrev_b32_e32 v6, 7, v6
	v_and_b32_e32 v64, 0x7f80, v6
	v_lshl_add_u64 v[4:5], s[24:25], 0, v[4:5]
	ds_read2_b32 v[6:7], v58 offset1:32
	v_lshl_add_u64 v[4:5], v[4:5], 0, v[64:65]
	v_lshl_add_u64 v[4:5], v[4:5], 0, v[44:45]
	global_store_dwordx4 v[4:5], v[0:3], off
	ds_read2_b32 v[4:5], v58 offset0:192 offset1:224
	s_waitcnt lgkmcnt(2)
	v_mul_f32_e32 v2, 0x44f00000, v56
	v_mul_f32_e32 v3, 0x44f00000, v57
	v_med3_f32 v2, v2, s44, v143
	s_waitcnt lgkmcnt(1)
	v_mul_f32_e32 v0, 0x44f00000, v6
	v_add_f32_e32 v6, 0x4b400000, v2
	v_med3_f32 v2, v3, s44, v143
	v_mul_f32_e32 v1, 0x44f00000, v7
	v_add_f32_e32 v7, 0x4b400000, v2
	ds_read2_b32 v[2:3], v58 offset0:128 offset1:160
	v_med3_f32 v0, v0, s44, v143
	v_med3_f32 v1, v1, s44, v143
	v_add_f32_e32 v0, 0x4b400000, v0
	v_add_f32_e32 v1, 0x4b400000, v1
	v_perm_b32 v0, v1, v0, s45
	v_perm_b32 v1, v7, v6, s45
	v_lshl_or_b32 v0, v1, 16, v0
	s_waitcnt lgkmcnt(0)
	v_mul_f32_e32 v1, 0x44f00000, v2
	v_mul_f32_e32 v2, 0x44f00000, v3
	v_mul_f32_e32 v3, 0x44f00000, v4
	v_med3_f32 v1, v1, s44, v143
	v_med3_f32 v2, v2, s44, v143
	v_mul_f32_e32 v4, 0x44f00000, v5
	v_add_f32_e32 v1, 0x4b400000, v1
	v_add_f32_e32 v5, 0x4b400000, v2
	v_med3_f32 v2, v3, s44, v143
	v_add_u32_e32 v56, 0x400, v58
	v_add_f32_e32 v6, 0x4b400000, v2
	v_med3_f32 v2, v4, s44, v143
	v_perm_b32 v1, v5, v1, s45
	ds_read2_b32 v[4:5], v56 offset0:64 offset1:96
	v_add_f32_e32 v7, 0x4b400000, v2
	ds_read2_b32 v[2:3], v56 offset1:32
	v_perm_b32 v6, v7, v6, s45
	v_lshl_or_b32 v1, v6, 16, v1
	s_waitcnt lgkmcnt(1)
	v_mul_f32_e32 v4, 0x44f00000, v4
	v_mul_f32_e32 v5, 0x44f00000, v5
	v_med3_f32 v4, v4, s44, v143
	v_add_f32_e32 v57, 0x4b400000, v4
	v_med3_f32 v4, v5, s44, v143
	v_add_f32_e32 v58, 0x4b400000, v4
	ds_read2_b32 v[4:5], v56 offset0:128 offset1:160
	ds_read2_b32 v[6:7], v56 offset0:192 offset1:224
	s_waitcnt lgkmcnt(2)
	v_mul_f32_e32 v2, 0x44f00000, v2
	v_mul_f32_e32 v3, 0x44f00000, v3
	v_med3_f32 v2, v2, s44, v143
	v_med3_f32 v3, v3, s44, v143
	v_add_f32_e32 v2, 0x4b400000, v2
	v_add_f32_e32 v3, 0x4b400000, v3
	v_perm_b32 v2, v3, v2, s45
	v_perm_b32 v3, v58, v57, s45
	v_lshl_or_b32 v2, v3, 16, v2
	s_waitcnt lgkmcnt(1)
	v_mul_f32_e32 v3, 0x44f00000, v4
	v_mul_f32_e32 v4, 0x44f00000, v5
	s_waitcnt lgkmcnt(0)
	v_mul_f32_e32 v5, 0x44f00000, v6
	v_mul_f32_e32 v6, 0x44f00000, v7
	v_med3_f32 v3, v3, s44, v143
	v_med3_f32 v4, v4, s44, v143
	v_med3_f32 v5, v5, s44, v143
	v_med3_f32 v6, v6, s44, v143
	v_add_f32_e32 v3, 0x4b400000, v3
	v_add_f32_e32 v4, 0x4b400000, v4
	v_add_f32_e32 v5, 0x4b400000, v5
	v_add_f32_e32 v6, 0x4b400000, v6
	v_perm_b32 v3, v4, v3, s45
	v_perm_b32 v4, v6, v5, s45
	v_add_u32_e32 v6, s0, v82
	v_lshl_or_b32 v3, v4, 16, v3
	v_ashrrev_i32_e32 v4, 3, v6
	v_and_b32_e32 v4, 0xffffffe0, v4
	v_add_u32_e32 v4, s9, v4
	v_add_u32_e32 v58, v88, v89
	v_ashrrev_i32_e32 v5, 31, v4
	ds_read2_b32 v[56:57], v58 offset0:64 offset1:96
	v_lshlrev_b64 v[4:5], 15, v[4:5]
	v_lshlrev_b32_e32 v6, 7, v6
	v_and_b32_e32 v64, 0x7f80, v6
	v_lshl_add_u64 v[4:5], s[24:25], 0, v[4:5]
	ds_read2_b32 v[6:7], v58 offset1:32
	v_lshl_add_u64 v[4:5], v[4:5], 0, v[64:65]
	v_lshl_add_u64 v[4:5], v[4:5], 0, v[44:45]
	global_store_dwordx4 v[4:5], v[0:3], off
	ds_read2_b32 v[4:5], v58 offset0:192 offset1:224
	s_waitcnt lgkmcnt(2)
	v_mul_f32_e32 v2, 0x44f00000, v56
	v_mul_f32_e32 v3, 0x44f00000, v57
	v_med3_f32 v2, v2, s44, v143
	s_waitcnt lgkmcnt(1)
	v_mul_f32_e32 v0, 0x44f00000, v6
	v_add_f32_e32 v6, 0x4b400000, v2
	v_med3_f32 v2, v3, s44, v143
	v_mul_f32_e32 v1, 0x44f00000, v7
	v_add_f32_e32 v7, 0x4b400000, v2
	ds_read2_b32 v[2:3], v58 offset0:128 offset1:160
	v_med3_f32 v0, v0, s44, v143
	v_med3_f32 v1, v1, s44, v143
	v_add_f32_e32 v0, 0x4b400000, v0
	v_add_f32_e32 v1, 0x4b400000, v1
	v_perm_b32 v0, v1, v0, s45
	v_perm_b32 v1, v7, v6, s45
	v_lshl_or_b32 v0, v1, 16, v0
	s_waitcnt lgkmcnt(0)
	v_mul_f32_e32 v1, 0x44f00000, v2
	v_mul_f32_e32 v2, 0x44f00000, v3
	v_mul_f32_e32 v3, 0x44f00000, v4
	v_med3_f32 v1, v1, s44, v143
	v_med3_f32 v2, v2, s44, v143
	v_mul_f32_e32 v4, 0x44f00000, v5
	v_add_f32_e32 v1, 0x4b400000, v1
	v_add_f32_e32 v5, 0x4b400000, v2
	v_med3_f32 v2, v3, s44, v143
	v_add_u32_e32 v56, 0x400, v58
	v_add_f32_e32 v6, 0x4b400000, v2
	v_med3_f32 v2, v4, s44, v143
	v_perm_b32 v1, v5, v1, s45
	ds_read2_b32 v[4:5], v56 offset0:64 offset1:96
	v_add_f32_e32 v7, 0x4b400000, v2
	ds_read2_b32 v[2:3], v56 offset1:32
	v_perm_b32 v6, v7, v6, s45
	v_lshl_or_b32 v1, v6, 16, v1
	s_waitcnt lgkmcnt(1)
	v_mul_f32_e32 v4, 0x44f00000, v4
	v_mul_f32_e32 v5, 0x44f00000, v5
	v_med3_f32 v4, v4, s44, v143
	v_add_f32_e32 v57, 0x4b400000, v4
	v_med3_f32 v4, v5, s44, v143
	v_add_f32_e32 v58, 0x4b400000, v4
	ds_read2_b32 v[4:5], v56 offset0:128 offset1:160
	ds_read2_b32 v[6:7], v56 offset0:192 offset1:224
	s_waitcnt lgkmcnt(2)
	v_mul_f32_e32 v2, 0x44f00000, v2
	v_mul_f32_e32 v3, 0x44f00000, v3
	v_med3_f32 v2, v2, s44, v143
	v_med3_f32 v3, v3, s44, v143
	v_add_f32_e32 v2, 0x4b400000, v2
	v_add_f32_e32 v3, 0x4b400000, v3
	v_perm_b32 v2, v3, v2, s45
	v_perm_b32 v3, v58, v57, s45
	v_lshl_or_b32 v2, v3, 16, v2
	s_waitcnt lgkmcnt(1)
	v_mul_f32_e32 v3, 0x44f00000, v4
	v_mul_f32_e32 v4, 0x44f00000, v5
	s_waitcnt lgkmcnt(0)
	v_mul_f32_e32 v5, 0x44f00000, v6
	v_mul_f32_e32 v6, 0x44f00000, v7
	v_med3_f32 v3, v3, s44, v143
	v_med3_f32 v4, v4, s44, v143
	v_med3_f32 v5, v5, s44, v143
	v_med3_f32 v6, v6, s44, v143
	v_add_f32_e32 v3, 0x4b400000, v3
	v_add_f32_e32 v4, 0x4b400000, v4
	v_add_f32_e32 v5, 0x4b400000, v5
	v_add_f32_e32 v6, 0x4b400000, v6
	v_perm_b32 v3, v4, v3, s45
	v_perm_b32 v4, v6, v5, s45
	v_add_u32_e32 v6, s0, v83
	v_lshl_or_b32 v3, v4, 16, v3
	v_ashrrev_i32_e32 v4, 3, v6
	v_and_b32_e32 v4, 0xffffffe0, v4
	v_add_u32_e32 v4, s9, v4
	v_ashrrev_i32_e32 v5, 31, v4
	v_lshlrev_b64 v[4:5], 15, v[4:5]
	v_lshlrev_b32_e32 v6, 7, v6
	v_and_b32_e32 v64, 0x7f80, v6
	v_lshl_add_u64 v[4:5], s[24:25], 0, v[4:5]
	v_lshl_add_u64 v[4:5], v[4:5], 0, v[64:65]
	v_lshl_add_u64 v[4:5], v[4:5], 0, v[44:45]
	global_store_dwordx4 v[4:5], v[0:3], off
	s_waitcnt lgkmcnt(0)
	s_branch .LBB0_33
